# attention unit end: the 14 serialized gate-row loads (load, vmcnt(0), store per row group) replaced by a 4-deep rolling prefetch with counted vmcnt
# speedup vs baseline: 1.0406x; 1.0091x over previous
; DI void attn_unit(LAS unsigned char* lds, const bf16_t* P, bf16_t* Am, int qrow0, int h, int ntiles, int krow_ctx, int krow_lat,
;                   float lam, const float* subw, float outscale) {
;     ...
;     if (n == 0) {
; #pragma unroll
;         for (int half = 0; half < 2; ++half) {
;             float ss = 0.f; const float inv = half ? invb : inva;
; #pragma unroll
;             for (int d0 = 0; d0 < 4; ++d0)
; #pragma unroll
;                 for (int r = 0; r < 16; ++r) { const float v = (half ? ob[d0][r] : oa[d0][r]) * inv - xch[half * 4096 + (d0 * 16 + r) * 64 + lane2]; if (half) ob[d0][r] = v; else oa[d0][r] = v; ss += v * v; }
;             ss = sum_x32(ss);
;             const float rr = rsqrtf(ss * (1.0f / 128.0f) + EPS) * outscale;
;             LAS float* stg = xch + half * 4096;
; #pragma unroll
;             for (int d0 = 0; d0 < 4; ++d0)
; #pragma unroll
;                 for (int rg = 0; rg < 4; ++rg) { const int e0 = 32 * d0 + 8 * rg, cc = 8 * d0 + 2 * rg + hie;
;                     const f32x4 w4 = *(const f32x4*)(subw + e0 + 4 * hie);
;                     const float v0 = half ? ob[d0][4 * rg + 0] : oa[d0][4 * rg + 0], v1 = half ? ob[d0][4 * rg + 1] : oa[d0][4 * rg + 1];
;                     const float v2 = half ? ob[d0][4 * rg + 2] : oa[d0][4 * rg + 2], v3 = half ? ob[d0][4 * rg + 3] : oa[d0][4 * rg + 3];
;                     const f32x4 tv = {v0 * rr * w4[0], v1 * rr * w4[1], v2 * rr * w4[2], v3 * rr * w4[3]};
;                     *(LAS f32x4*)(stg + r32e * 128 + ((cc ^ r32e) & 31) * 4) = tv; }
;             const int k16 = lane2 & 15;
; #pragma unroll
;             for (int i = 0; i < 8; ++i) { const int R = 4 * i + (lane2 >> 4);
;                 const f32x4 ta = *(const LAS f32x4*)(stg + R * 128 + (((2 * k16) ^ R) & 31) * 4), tb = *(const LAS f32x4*)(stg + R * 128 + (((2 * k16 + 1) ^ R) & 31) * 4);
;                 const size_t row = (size_t)(qrow0 + 64 * g + 32 * half + R);
;                 const u32x4 sg = *(const u32x4*)(P + row * DIN + O_AG + h * 128 + 8 * k16);
;                 u32x4 ov; ov.x = cvtpk(ta[0] * bf_lo(sg.x), ta[1] * bf_hi(sg.x)); ov.y = cvtpk(ta[2] * bf_lo(sg.y), ta[3] * bf_hi(sg.y));
;                 ov.z = cvtpk(tb[0] * bf_lo(sg.z), tb[1] * bf_hi(sg.z)); ov.w = cvtpk(tb[2] * bf_lo(sg.w), tb[3] * bf_hi(sg.w));
;                 *(u32x4*)(Am + row * DM + 1024 + h * 128 + 8 * k16) = ov; }
.LBB0_336:
	s_cmpk_gt_u32 s31, 0xff
	s_waitcnt lgkmcnt(0)
	s_barrier
	s_cbranch_scc1 .LBB0_325
	s_lshl_b32 s8, s17, 1
	s_add_i32 s8, s8, s86
	s_add_u32 s8, s50, s8
	s_addc_u32 s9, s51, 0
	v_and_b32_e32 v244, 63, v220
	v_lshrrev_b32_e32 v245, 4, v244
	v_add_u32_e32 v245, s16, v245
	v_mul_lo_u32 v245, v245, s87
	v_and_b32_e32 v244, 15, v244
	v_lshl_add_u32 v244, v244, 4, v245
	s_add_u32 s6, s8, 0xc000
	s_addc_u32 s7, s9, 0
	global_load_dwordx4 v[228:231], v244, s[6:7] offset:2048
	s_add_u32 s6, s8, 0x18000
	s_addc_u32 s7, s9, 0
	global_load_dwordx4 v[232:235], v244, s[6:7] offset:2048
	s_add_u32 s6, s8, 0x24000
	s_addc_u32 s7, s9, 0
	global_load_dwordx4 v[236:239], v244, s[6:7] offset:2048
	s_add_u32 s6, s8, 0x30000
	s_addc_u32 s7, s9, 0
	global_load_dwordx4 v[240:243], v244, s[6:7] offset:2048
	v_lshlrev_b32_e32 v130, 9, v128
	v_and_b32_e32 v134, 0x3e00, v130
	ds_read2st64_b32 v[130:131], v214 offset1:1
	ds_read2st64_b32 v[132:133], v214 offset0:2 offset1:3
	ds_read2st64_b32 v[140:141], v214 offset0:4 offset1:5
	ds_read2st64_b32 v[142:143], v214 offset0:6 offset1:7
	ds_read2st64_b32 v[144:145], v214 offset0:8 offset1:9
	ds_read2st64_b32 v[146:147], v214 offset0:10 offset1:11
	ds_read2st64_b32 v[148:149], v214 offset0:12 offset1:13
	ds_read2st64_b32 v[150:151], v214 offset0:14 offset1:15
	ds_read2st64_b32 v[152:153], v214 offset0:16 offset1:17
	ds_read2st64_b32 v[154:155], v214 offset0:18 offset1:19
	ds_read2st64_b32 v[156:157], v214 offset0:20 offset1:21
	ds_read2st64_b32 v[158:159], v214 offset0:22 offset1:23
	ds_read2st64_b32 v[160:161], v214 offset0:24 offset1:25
	ds_read2st64_b32 v[162:163], v214 offset0:26 offset1:27
	ds_read2st64_b32 v[164:165], v214 offset0:28 offset1:29
	ds_read2st64_b32 v[166:167], v214 offset0:30 offset1:31
	ds_read2st64_b32 v[208:209], v214 offset0:32 offset1:33
	ds_read2st64_b32 v[210:211], v214 offset0:34 offset1:35
	ds_read2st64_b32 v[212:213], v214 offset0:36 offset1:37
	ds_read2st64_b32 v[224:225], v214 offset0:38 offset1:39
	ds_read2st64_b32 v[226:227], v214 offset0:40 offset1:41
	ds_read2st64_b32 v[168:169], v214 offset0:42 offset1:43
	ds_read2st64_b32 v[170:171], v214 offset0:44 offset1:45
	ds_read2st64_b32 v[172:173], v214 offset0:46 offset1:47
	ds_read2st64_b32 v[174:175], v214 offset0:48 offset1:49
	ds_read2st64_b32 v[178:179], v214 offset0:50 offset1:51
	ds_read2st64_b32 v[186:187], v214 offset0:52 offset1:53
	ds_read2st64_b32 v[194:195], v214 offset0:54 offset1:55
	ds_read2st64_b32 v[198:199], v214 offset0:56 offset1:57
	ds_read2st64_b32 v[196:197], v214 offset0:58 offset1:59
	ds_read2st64_b32 v[192:193], v214 offset0:60 offset1:61
	ds_read2st64_b32 v[184:185], v214 offset0:62 offset1:63
	s_waitcnt lgkmcnt(14)
	v_pk_fma_f32 v[176:177], v[112:113], v[138:139], v[130:131] op_sel_hi:[1,0,1] neg_lo:[0,0,1] neg_hi:[0,0,1]
	v_lshrrev_b32_e32 v216, 5, v129
	v_mul_f32_e32 v112, v177, v177
	v_pk_fma_f32 v[112:113], v[176:177], v[176:177], v[112:113] op_sel_hi:[1,1,0]
	v_pk_fma_f32 v[180:181], v[114:115], v[138:139], v[132:133] op_sel_hi:[1,0,1] neg_lo:[0,0,1] neg_hi:[0,0,1]
	v_lshlrev_b32_e32 v204, 4, v216
	v_pk_fma_f32 v[112:113], v[180:181], v[180:181], v[112:113]
	v_mul_f32_e32 v114, v181, v181
	v_and_b32_e32 v217, 31, v128
	v_and_b32_e32 v218, 15, v128
	v_lshrrev_b32_e32 v137, 4, v129
	v_add_u32_e32 v219, s0, v134
	v_pk_add_f32 v[112:113], v[112:113], v[114:115] op_sel_hi:[1,0]
	v_bitop3_b32 v114, v216, v128, 31 bitop3:0x78
	global_load_dwordx4 v[132:135], v204, s[36:37]
	global_load_dwordx4 v[128:131], v204, s[36:37] offset:32
	v_lshl_add_u32 v139, v114, 4, v219
	v_pk_fma_f32 v[182:183], v[116:117], v[138:139], v[140:141] op_sel_hi:[1,0,1] neg_lo:[0,0,1] neg_hi:[0,0,1]
	v_pk_fma_f32 v[188:189], v[118:119], v[138:139], v[142:143] op_sel_hi:[1,0,1] neg_lo:[0,0,1] neg_hi:[0,0,1]
	v_pk_fma_f32 v[112:113], v[182:183], v[182:183], v[112:113]
	v_mul_f32_e32 v114, v183, v183
	v_pk_add_f32 v[112:113], v[112:113], v[114:115] op_sel_hi:[1,0]
	v_mul_f32_e32 v114, v189, v189
	v_pk_fma_f32 v[112:113], v[188:189], v[188:189], v[112:113]
	v_pk_fma_f32 v[190:191], v[120:121], v[138:139], v[144:145] op_sel_hi:[1,0,1] neg_lo:[0,0,1] neg_hi:[0,0,1]
	v_pk_add_f32 v[112:113], v[112:113], v[114:115] op_sel_hi:[1,0]
	v_bitop3_b32 v114, v216, v217, 2 bitop3:0x36
	v_lshl_add_u32 v200, v114, 4, v219
	v_pk_fma_f32 v[112:113], v[190:191], v[190:191], v[112:113]
	v_mul_f32_e32 v114, v191, v191
	v_pk_add_f32 v[112:113], v[112:113], v[114:115] op_sel_hi:[1,0]
	v_pk_fma_f32 v[140:141], v[122:123], v[138:139], v[146:147] op_sel_hi:[1,0,1] neg_lo:[0,0,1] neg_hi:[0,0,1]
	v_pk_fma_f32 v[124:125], v[124:125], v[138:139], v[148:149] op_sel_hi:[1,0,1] neg_lo:[0,0,1] neg_hi:[0,0,1]
	v_pk_fma_f32 v[112:113], v[140:141], v[140:141], v[112:113]
	v_mul_f32_e32 v114, v141, v141
	v_pk_add_f32 v[120:121], v[112:113], v[114:115] op_sel_hi:[1,0]
	v_mul_f32_e32 v122, v125, v125
	v_pk_fma_f32 v[120:121], v[124:125], v[124:125], v[120:121]
	v_pk_fma_f32 v[126:127], v[126:127], v[138:139], v[150:151] op_sel_hi:[1,0,1] neg_lo:[0,0,1] neg_hi:[0,0,1]
	v_pk_add_f32 v[120:121], v[120:121], v[122:123] op_sel_hi:[1,0]
	v_mul_f32_e32 v122, v127, v127
	v_pk_fma_f32 v[120:121], v[126:127], v[126:127], v[120:121]
	v_pk_fma_f32 v[142:143], v[96:97], v[138:139], v[152:153] op_sel_hi:[1,0,1] neg_lo:[0,0,1] neg_hi:[0,0,1]
	v_pk_add_f32 v[120:121], v[120:121], v[122:123] op_sel_hi:[1,0]
	v_pk_fma_f32 v[144:145], v[98:99], v[138:139], v[154:155] op_sel_hi:[1,0,1] neg_lo:[0,0,1] neg_hi:[0,0,1]
	v_pk_fma_f32 v[96:97], v[142:143], v[142:143], v[120:121]
	v_mul_f32_e32 v120, v143, v143
	v_pk_add_f32 v[96:97], v[96:97], v[120:121] op_sel_hi:[1,0]
	v_mul_f32_e32 v98, v145, v145
; #define LAS __attribute__((address_space(3)))
; DI void attn_unit(LAS unsigned char* lds, const bf16_t* P, bf16_t* Am, int qrow0, int h, int ntiles, int krow_ctx, int krow_lat,
;                   float lam, const float* subw, float outscale) {
;     ...
;             for (int d0 = 0; d0 < 4; ++d0)
; #pragma unroll
;                 for (int r = 0; r < 16; ++r) { const float v = (half ? ob[d0][r] : oa[d0][r]) * inv - xch[half * 4096 + (d0 * 16 + r) * 64 + lane2]; if (half) ob[d0][r] = v; else oa[d0][r] = v; ss += v * v; }
;             ss = sum_x32(ss);
;             const float rr = rsqrtf(ss * (1.0f / 128.0f) + EPS) * outscale;
;             LAS float* stg = xch + half * 4096;
; #pragma unroll
;             for (int d0 = 0; d0 < 4; ++d0)
; #pragma unroll
;                 for (int rg = 0; rg < 4; ++rg) { const int e0 = 32 * d0 + 8 * rg, cc = 8 * d0 + 2 * rg + hie;
;                     const f32x4 w4 = *(const f32x4*)(subw + e0 + 4 * hie);
	v_pk_fma_f32 v[96:97], v[144:145], v[144:145], v[96:97]
	v_pk_fma_f32 v[146:147], v[100:101], v[138:139], v[156:157] op_sel_hi:[1,0,1] neg_lo:[0,0,1] neg_hi:[0,0,1]
	v_pk_add_f32 v[148:149], v[96:97], v[98:99] op_sel_hi:[1,0]
	v_pk_fma_f32 v[150:151], v[104:105], v[138:139], v[160:161] op_sel_hi:[1,0,1] neg_lo:[0,0,1] neg_hi:[0,0,1]
	v_pk_fma_f32 v[100:101], v[146:147], v[146:147], v[148:149]
	v_mul_f32_e32 v148, v147, v147
	v_pk_add_f32 v[100:101], v[100:101], v[148:149] op_sel_hi:[1,0]
	v_pk_fma_f32 v[148:149], v[102:103], v[138:139], v[158:159] op_sel_hi:[1,0,1] neg_lo:[0,0,1] neg_hi:[0,0,1]
	v_pk_fma_f32 v[152:153], v[106:107], v[138:139], v[162:163] op_sel_hi:[1,0,1] neg_lo:[0,0,1] neg_hi:[0,0,1]
	v_pk_fma_f32 v[100:101], v[148:149], v[148:149], v[100:101]
	v_mul_f32_e32 v102, v149, v149
	v_pk_add_f32 v[100:101], v[100:101], v[102:103] op_sel_hi:[1,0]
	v_bitop3_b32 v102, v216, v217, 10 bitop3:0x36
	v_lshl_add_u32 v205, v102, 4, v219
	v_pk_fma_f32 v[100:101], v[150:151], v[150:151], v[100:101]
	v_mul_f32_e32 v102, v151, v151
	v_pk_add_f32 v[100:101], v[100:101], v[102:103] op_sel_hi:[1,0]
	v_mul_f32_e32 v102, v153, v153
	v_pk_fma_f32 v[100:101], v[152:153], v[152:153], v[100:101]
	v_pk_fma_f32 v[154:155], v[108:109], v[138:139], v[164:165] op_sel_hi:[1,0,1] neg_lo:[0,0,1] neg_hi:[0,0,1]
	v_pk_add_f32 v[156:157], v[100:101], v[102:103] op_sel_hi:[1,0]
	v_pk_fma_f32 v[158:159], v[80:81], v[138:139], v[208:209] op_sel_hi:[1,0,1] neg_lo:[0,0,1] neg_hi:[0,0,1]
	v_pk_fma_f32 v[108:109], v[154:155], v[154:155], v[156:157]
	v_mul_f32_e32 v156, v155, v155
	v_pk_add_f32 v[108:109], v[108:109], v[156:157] op_sel_hi:[1,0]
	v_pk_fma_f32 v[156:157], v[110:111], v[138:139], v[166:167] op_sel_hi:[1,0,1] neg_lo:[0,0,1] neg_hi:[0,0,1]
	v_pk_fma_f32 v[160:161], v[82:83], v[138:139], v[210:211] op_sel_hi:[1,0,1] neg_lo:[0,0,1] neg_hi:[0,0,1]
	v_pk_fma_f32 v[108:109], v[156:157], v[156:157], v[108:109]
	v_mul_f32_e32 v110, v157, v157
	v_pk_add_f32 v[108:109], v[108:109], v[110:111] op_sel_hi:[1,0]
	v_mul_f32_e32 v82, v161, v161
	v_pk_fma_f32 v[80:81], v[158:159], v[158:159], v[108:109]
	v_mul_f32_e32 v108, v159, v159
	v_pk_add_f32 v[80:81], v[80:81], v[108:109] op_sel_hi:[1,0]
	s_waitcnt lgkmcnt(13)
	v_pk_fma_f32 v[162:163], v[84:85], v[138:139], v[212:213] op_sel_hi:[1,0,1] neg_lo:[0,0,1] neg_hi:[0,0,1]
	v_pk_fma_f32 v[80:81], v[160:161], v[160:161], v[80:81]
	s_waitcnt lgkmcnt(11)
	v_pk_fma_f32 v[166:167], v[88:89], v[138:139], v[226:227] op_sel_hi:[1,0,1] neg_lo:[0,0,1] neg_hi:[0,0,1]
	v_pk_add_f32 v[164:165], v[80:81], v[82:83] op_sel_hi:[1,0]
	s_waitcnt lgkmcnt(10)
	v_pk_fma_f32 v[168:169], v[90:91], v[138:139], v[168:169] op_sel_hi:[1,0,1] neg_lo:[0,0,1] neg_hi:[0,0,1]
	v_pk_fma_f32 v[84:85], v[162:163], v[162:163], v[164:165]
	v_mul_f32_e32 v164, v163, v163
	v_pk_add_f32 v[84:85], v[84:85], v[164:165] op_sel_hi:[1,0]
	v_pk_fma_f32 v[164:165], v[86:87], v[138:139], v[224:225] op_sel_hi:[1,0,1] neg_lo:[0,0,1] neg_hi:[0,0,1]
	s_waitcnt lgkmcnt(9)
	v_pk_fma_f32 v[170:171], v[92:93], v[138:139], v[170:171] op_sel_hi:[1,0,1] neg_lo:[0,0,1] neg_hi:[0,0,1]
	v_pk_fma_f32 v[84:85], v[164:165], v[164:165], v[84:85]
	v_mul_f32_e32 v86, v165, v165
	v_pk_add_f32 v[84:85], v[84:85], v[86:87] op_sel_hi:[1,0]
	v_bitop3_b32 v86, v216, v217, 18 bitop3:0x36
	v_lshl_add_u32 v209, v86, 4, v219
	v_pk_fma_f32 v[84:85], v[166:167], v[166:167], v[84:85]
	v_mul_f32_e32 v86, v167, v167
	v_pk_add_f32 v[84:85], v[84:85], v[86:87] op_sel_hi:[1,0]
	v_mul_f32_e32 v86, v169, v169
	v_pk_fma_f32 v[84:85], v[168:169], v[168:169], v[84:85]
	s_waitcnt lgkmcnt(8)
	v_pk_fma_f32 v[172:173], v[94:95], v[138:139], v[172:173] op_sel_hi:[1,0,1] neg_lo:[0,0,1] neg_hi:[0,0,1]
	v_pk_add_f32 v[212:213], v[84:85], v[86:87] op_sel_hi:[1,0]
	v_mul_f32_e32 v94, v173, v173
	v_pk_fma_f32 v[92:93], v[170:171], v[170:171], v[212:213]
	v_mul_f32_e32 v212, v171, v171
	v_pk_add_f32 v[92:93], v[92:93], v[212:213] op_sel_hi:[1,0]
	s_waitcnt lgkmcnt(7)
	v_pk_fma_f32 v[174:175], v[64:65], v[138:139], v[174:175] op_sel_hi:[1,0,1] neg_lo:[0,0,1] neg_hi:[0,0,1]
	v_pk_fma_f32 v[92:93], v[172:173], v[172:173], v[92:93]
	s_waitcnt lgkmcnt(6)
	v_pk_fma_f32 v[178:179], v[66:67], v[138:139], v[178:179] op_sel_hi:[1,0,1] neg_lo:[0,0,1] neg_hi:[0,0,1]
	v_pk_add_f32 v[92:93], v[92:93], v[94:95] op_sel_hi:[1,0]
	v_mul_f32_e32 v66, v179, v179
	v_pk_fma_f32 v[64:65], v[174:175], v[174:175], v[92:93]
	v_mul_f32_e32 v92, v175, v175
	v_pk_add_f32 v[64:65], v[64:65], v[92:93] op_sel_hi:[1,0]
	s_waitcnt lgkmcnt(5)
	v_pk_fma_f32 v[186:187], v[68:69], v[138:139], v[186:187] op_sel_hi:[1,0,1] neg_lo:[0,0,1] neg_hi:[0,0,1]
	v_pk_fma_f32 v[64:65], v[178:179], v[178:179], v[64:65]
	v_mul_f32_e32 v222, v187, v187
	v_pk_add_f32 v[224:225], v[64:65], v[66:67] op_sel_hi:[1,0]
	v_bitop3_b32 v112, v216, v217, 4 bitop3:0x36
	v_pk_fma_f32 v[68:69], v[186:187], v[186:187], v[224:225]
	s_waitcnt lgkmcnt(4)
	v_pk_fma_f32 v[194:195], v[70:71], v[138:139], v[194:195] op_sel_hi:[1,0,1] neg_lo:[0,0,1] neg_hi:[0,0,1]
	v_pk_add_f32 v[68:69], v[68:69], v[222:223] op_sel_hi:[1,0]
	v_lshl_add_u32 v201, v112, 4, v219
	global_load_dwordx4 v[116:119], v204, s[36:37] offset:64
	global_load_dwordx4 v[112:115], v204, s[36:37] offset:96
	v_pk_fma_f32 v[68:69], v[194:195], v[194:195], v[68:69]
	v_mul_f32_e32 v70, v195, v195
	v_pk_add_f32 v[68:69], v[68:69], v[70:71] op_sel_hi:[1,0]
	v_bitop3_b32 v70, v216, v217, 26 bitop3:0x36
	s_waitcnt lgkmcnt(3)
	v_pk_fma_f32 v[198:199], v[72:73], v[138:139], v[198:199] op_sel_hi:[1,0,1] neg_lo:[0,0,1] neg_hi:[0,0,1]
	v_lshl_add_u32 v213, v70, 4, v219
	v_pk_fma_f32 v[68:69], v[198:199], v[198:199], v[68:69]
	v_mul_f32_e32 v70, v199, v199
	v_bitop3_b32 v122, v216, v217, 6 bitop3:0x36
	v_bitop3_b32 v96, v216, v217, 8 bitop3:0x36
	v_pk_add_f32 v[68:69], v[68:69], v[70:71] op_sel_hi:[1,0]
	s_waitcnt lgkmcnt(2)
; #define LAS __attribute__((address_space(3)))
; DI void attn_unit(LAS unsigned char* lds, const bf16_t* P, bf16_t* Am, int qrow0, int h, int ntiles, int krow_ctx, int krow_lat,
;                   float lam, const float* subw, float outscale) {
;     ...
;             ss = sum_x32(ss);
;             const float rr = rsqrtf(ss * (1.0f / 128.0f) + EPS) * outscale;
;             LAS float* stg = xch + half * 4096;
; #pragma unroll
;             for (int d0 = 0; d0 < 4; ++d0)
; #pragma unroll
;                 for (int rg = 0; rg < 4; ++rg) { const int e0 = 32 * d0 + 8 * rg, cc = 8 * d0 + 2 * rg + hie;
;                     const f32x4 w4 = *(const f32x4*)(subw + e0 + 4 * hie);
;                     const float v0 = half ? ob[d0][4 * rg + 0] : oa[d0][4 * rg + 0], v1 = half ? ob[d0][4 * rg + 1] : oa[d0][4 * rg + 1];
;                     const float v2 = half ? ob[d0][4 * rg + 2] : oa[d0][4 * rg + 2], v3 = half ? ob[d0][4 * rg + 3] : oa[d0][4 * rg + 3];
;                     const f32x4 tv = {v0 * rr * w4[0], v1 * rr * w4[1], v2 * rr * w4[2], v3 * rr * w4[3]};
;                     *(LAS f32x4*)(stg + r32e * 128 + ((cc ^ r32e) & 31) * 4) = tv; }
;             const int k16 = lane2 & 15;
; #pragma unroll
;             for (int i = 0; i < 8; ++i) { const int R = 4 * i + (lane2 >> 4);
;                 const f32x4 ta = *(const LAS f32x4*)(stg + R * 128 + (((2 * k16) ^ R) & 31) * 4), tb = *(const LAS f32x4*)(stg + R * 128 + (((2 * k16 + 1) ^ R) & 31) * 4);
	v_pk_fma_f32 v[196:197], v[74:75], v[138:139], v[196:197] op_sel_hi:[1,0,1] neg_lo:[0,0,1] neg_hi:[0,0,1]
	v_lshl_add_u32 v202, v122, 4, v219
	v_lshl_add_u32 v203, v96, 4, v219
	global_load_dwordx4 v[120:123], v204, s[36:37] offset:128
	global_load_dwordx4 v[96:99], v204, s[36:37] offset:160
	v_pk_fma_f32 v[68:69], v[196:197], v[196:197], v[68:69]
	v_mul_f32_e32 v70, v197, v197
	v_pk_add_f32 v[68:69], v[68:69], v[70:71] op_sel_hi:[1,0]
	s_waitcnt lgkmcnt(1)
	v_pk_fma_f32 v[192:193], v[76:77], v[138:139], v[192:193] op_sel_hi:[1,0,1] neg_lo:[0,0,1] neg_hi:[0,0,1]
	v_bitop3_b32 v71, v216, v217, 28 bitop3:0x36
	v_pk_fma_f32 v[68:69], v[192:193], v[192:193], v[68:69]
	v_mul_f32_e32 v70, v193, v193
	v_bitop3_b32 v100, v216, v217, 12 bitop3:0x36
	v_pk_add_f32 v[68:69], v[68:69], v[70:71] op_sel_hi:[1,0]
	s_waitcnt lgkmcnt(0)
	v_pk_fma_f32 v[78:79], v[78:79], v[138:139], v[184:185] op_sel_hi:[1,0,1] neg_lo:[0,0,1] neg_hi:[0,0,1]
	v_lshl_add_u32 v206, v100, 4, v219
	global_load_dwordx4 v[104:107], v204, s[36:37] offset:192
	global_load_dwordx4 v[100:103], v204, s[36:37] offset:224
	v_pk_fma_f32 v[68:69], v[78:79], v[78:79], v[68:69]
	v_mul_f32_e32 v70, v79, v79
	v_pk_add_f32 v[68:69], v[68:69], v[70:71] op_sel_hi:[1,0]
	v_bitop3_b32 v110, v216, v217, 14 bitop3:0x36
	v_mov_b32_e32 v69, v68
	v_bitop3_b32 v80, v216, v217, 16 bitop3:0x36
	s_nop 0
	v_permlane32_swap_b32_e32 v68, v69
	v_lshl_add_u32 v207, v110, 4, v219
	v_lshl_add_u32 v208, v80, 4, v219
	global_load_dwordx4 v[108:111], v204, s[36:37] offset:256
	global_load_dwordx4 v[80:83], v204, s[36:37] offset:288
	v_add_f32_e32 v68, v68, v69
	v_fmamk_f32 v68, v68, 0x3c000000, v221
	v_mul_f32_e32 v69, 0x4b800000, v68
	v_cmp_gt_f32_e32 vcc, s85, v68
	v_bitop3_b32 v84, v216, v217, 20 bitop3:0x36
	v_lshl_add_u32 v210, v84, 4, v219
	v_cndmask_b32_e32 v68, v68, v69, vcc
	global_load_dwordx4 v[88:91], v204, s[36:37] offset:320
	global_load_dwordx4 v[84:87], v204, s[36:37] offset:352
	v_rsq_f32_e32 v76, v68
	v_bitop3_b32 v94, v216, v217, 22 bitop3:0x36
	v_bitop3_b32 v64, v216, v217, 24 bitop3:0x36
	v_lshl_add_u32 v211, v94, 4, v219
	v_lshl_add_u32 v212, v64, 4, v219
	global_load_dwordx4 v[92:95], v204, s[36:37] offset:384
	global_load_dwordx4 v[64:67], v204, s[36:37] offset:416
	v_mul_f32_e32 v77, 0x45800000, v76
	v_cndmask_b32_e32 v76, v76, v77, vcc
	v_mul_f32_e32 v138, v250, v76
	v_pk_mul_f32 v[76:77], v[176:177], v[138:139] op_sel_hi:[1,0]
	v_pk_mul_f32 v[176:177], v[180:181], v[138:139] op_sel_hi:[1,0]
	v_lshl_add_u32 v184, v71, 4, v219
	global_load_dwordx4 v[72:75], v204, s[36:37] offset:448
	global_load_dwordx4 v[68:71], v204, s[36:37] offset:480
	s_waitcnt vmcnt(15)
	v_pk_mul_f32 v[134:135], v[134:135], v[176:177]
	v_pk_mul_f32 v[132:133], v[132:133], v[76:77]
	ds_write_b128 v139, v[132:135]
	v_pk_mul_f32 v[76:77], v[182:183], v[138:139] op_sel_hi:[1,0]
	v_pk_mul_f32 v[132:133], v[188:189], v[138:139] op_sel_hi:[1,0]
	s_waitcnt vmcnt(14)
	v_pk_mul_f32 v[128:129], v[128:129], v[76:77]
	v_pk_mul_f32 v[130:131], v[130:131], v[132:133]
	v_add_u32_e32 v134, s16, v137
	v_mov_b64_e32 v[76:77], s[50:51]
	ds_write_b128 v200, v[128:131]
	v_mad_i64_i32 v[128:129], s[4:5], v134, s87, v[76:77]
	s_lshl_b32 s42, s17, 1
	v_lshl_add_u64 v[128:129], v[128:129], 0, s[42:43]
	v_lshlrev_b32_e32 v222, 4, v218
	v_lshl_add_u64 v[128:129], v[128:129], 0, v[222:223]
	v_add_co_u32_e32 v128, vcc, s86, v128
	v_pk_mul_f32 v[132:133], v[190:191], v[138:139] op_sel_hi:[1,0]
	s_nop 0
	v_addc_co_u32_e32 v129, vcc, 0, v129, vcc
	global_load_dwordx4 v[128:131], v[128:129], off offset:2048
	v_pk_mul_f32 v[140:141], v[140:141], v[138:139] op_sel_hi:[1,0]
	s_waitcnt vmcnt(14)
	v_pk_mul_f32 v[116:117], v[116:117], v[132:133]
	v_pk_mul_f32 v[118:119], v[118:119], v[140:141]
	ds_write_b128 v201, v[116:119]
	v_pk_mul_f32 v[116:117], v[124:125], v[138:139] op_sel_hi:[1,0]
	v_pk_mul_f32 v[118:119], v[126:127], v[138:139] op_sel_hi:[1,0]
	s_waitcnt vmcnt(13)
	v_pk_mul_f32 v[112:113], v[112:113], v[116:117]
	v_pk_mul_f32 v[114:115], v[114:115], v[118:119]
	ds_write_b128 v202, v[112:115]
	v_pk_mul_f32 v[112:113], v[142:143], v[138:139] op_sel_hi:[1,0]
	v_pk_mul_f32 v[114:115], v[144:145], v[138:139] op_sel_hi:[1,0]
	v_lshlrev_b32_e32 v215, 1, v218
	s_waitcnt vmcnt(12)
	v_pk_mul_f32 v[114:115], v[122:123], v[114:115]
	v_pk_mul_f32 v[112:113], v[120:121], v[112:113]
	ds_write_b128 v203, v[112:115]
	v_pk_mul_f32 v[112:113], v[146:147], v[138:139] op_sel_hi:[1,0]
	v_pk_mul_f32 v[114:115], v[148:149], v[138:139] op_sel_hi:[1,0]
	s_waitcnt vmcnt(11)
	v_pk_mul_f32 v[96:97], v[96:97], v[112:113]
	v_pk_mul_f32 v[98:99], v[98:99], v[114:115]
	ds_write_b128 v205, v[96:99]
	v_pk_mul_f32 v[96:97], v[150:151], v[138:139] op_sel_hi:[1,0]
	v_pk_mul_f32 v[98:99], v[152:153], v[138:139] op_sel_hi:[1,0]
	v_ashrrev_i32_e32 v135, 31, v134
	v_or_b32_e32 v144, 4, v137
	s_waitcnt vmcnt(10)
	v_pk_mul_f32 v[98:99], v[98:99], v[106:107]
	v_pk_mul_f32 v[96:97], v[96:97], v[104:105]
	ds_write_b128 v206, v[96:99]
	v_pk_mul_f32 v[96:97], v[154:155], v[138:139] op_sel_hi:[1,0]
	v_pk_mul_f32 v[98:99], v[156:157], v[138:139] op_sel_hi:[1,0]
	s_waitcnt vmcnt(9)
	v_pk_mul_f32 v[96:97], v[96:97], v[100:101]
	v_pk_mul_f32 v[98:99], v[98:99], v[102:103]
	ds_write_b128 v207, v[96:99]
	v_pk_mul_f32 v[96:97], v[158:159], v[138:139] op_sel_hi:[1,0]
	v_pk_mul_f32 v[98:99], v[160:161], v[138:139] op_sel_hi:[1,0]
	v_or_b32_e32 v147, 8, v137
	s_waitcnt vmcnt(8)
	v_pk_mul_f32 v[98:99], v[98:99], v[110:111]
	v_pk_mul_f32 v[96:97], v[96:97], v[108:109]
	ds_write_b128 v208, v[96:99]
	v_pk_mul_f32 v[96:97], v[162:163], v[138:139] op_sel_hi:[1,0]
	v_pk_mul_f32 v[98:99], v[164:165], v[138:139] op_sel_hi:[1,0]
	s_waitcnt vmcnt(7)
; #define LAS __attribute__((address_space(3)))
; DI unsigned cvtpk(float lo, float hi) { f32x2 v = {lo, hi}; bf16x2_t b = __builtin_convertvector(v, bf16x2_t); return __builtin_bit_cast(unsigned, b); }
; DI void attn_unit(LAS unsigned char* lds, const bf16_t* P, bf16_t* Am, int qrow0, int h, int ntiles, int krow_ctx, int krow_lat,
;                   float lam, const float* subw, float outscale) {
;     ...
;             const int k16 = lane2 & 15;
; #pragma unroll
;             for (int i = 0; i < 8; ++i) { const int R = 4 * i + (lane2 >> 4);
;                 const f32x4 ta = *(const LAS f32x4*)(stg + R * 128 + (((2 * k16) ^ R) & 31) * 4), tb = *(const LAS f32x4*)(stg + R * 128 + (((2 * k16 + 1) ^ R) & 31) * 4);
;                 const size_t row = (size_t)(qrow0 + 64 * g + 32 * half + R);
;                 const u32x4 sg = *(const u32x4*)(P + row * DIN + O_AG + h * 128 + 8 * k16);
;                 u32x4 ov; ov.x = cvtpk(ta[0] * bf_lo(sg.x), ta[1] * bf_hi(sg.x)); ov.y = cvtpk(ta[2] * bf_lo(sg.y), ta[3] * bf_hi(sg.y));
;                 ov.z = cvtpk(tb[0] * bf_lo(sg.z), tb[1] * bf_hi(sg.z)); ov.w = cvtpk(tb[2] * bf_lo(sg.w), tb[3] * bf_hi(sg.w));
;                 *(u32x4*)(Am + row * DM + 1024 + h * 128 + 8 * k16) = ov; }
	v_pk_mul_f32 v[80:81], v[96:97], v[80:81]
	v_pk_mul_f32 v[82:83], v[98:99], v[82:83]
	ds_write_b128 v209, v[80:83]
	v_pk_mul_f32 v[80:81], v[166:167], v[138:139] op_sel_hi:[1,0]
	v_pk_mul_f32 v[82:83], v[168:169], v[138:139] op_sel_hi:[1,0]
	s_waitcnt vmcnt(6)
	v_pk_mul_f32 v[80:81], v[80:81], v[88:89]
	v_pk_mul_f32 v[82:83], v[82:83], v[90:91]
	ds_write_b128 v210, v[80:83]
	v_pk_mul_f32 v[80:81], v[170:171], v[138:139] op_sel_hi:[1,0]
	v_pk_mul_f32 v[82:83], v[172:173], v[138:139] op_sel_hi:[1,0]
	s_waitcnt vmcnt(5)
	v_pk_mul_f32 v[80:81], v[80:81], v[84:85]
	v_pk_mul_f32 v[82:83], v[82:83], v[86:87]
	ds_write_b128 v211, v[80:83]
	v_pk_mul_f32 v[80:81], v[174:175], v[138:139] op_sel_hi:[1,0]
	v_pk_mul_f32 v[82:83], v[178:179], v[138:139] op_sel_hi:[1,0]
	s_waitcnt vmcnt(4)
	v_pk_mul_f32 v[80:81], v[80:81], v[92:93]
	v_pk_mul_f32 v[82:83], v[82:83], v[94:95]
	ds_write_b128 v212, v[80:83]
	v_pk_mul_f32 v[80:81], v[186:187], v[138:139] op_sel_hi:[1,0]
	v_pk_mul_f32 v[82:83], v[194:195], v[138:139] op_sel_hi:[1,0]
	s_waitcnt vmcnt(3)
	v_pk_mul_f32 v[64:65], v[80:81], v[64:65]
	v_pk_mul_f32 v[66:67], v[82:83], v[66:67]
	ds_write_b128 v213, v[64:67]
	v_pk_mul_f32 v[64:65], v[198:199], v[138:139] op_sel_hi:[1,0]
	v_pk_mul_f32 v[66:67], v[196:197], v[138:139] op_sel_hi:[1,0]
	s_waitcnt vmcnt(2)
	v_pk_mul_f32 v[64:65], v[64:65], v[72:73]
	v_pk_mul_f32 v[66:67], v[66:67], v[74:75]
	ds_write_b128 v184, v[64:67]
	v_pk_mul_f32 v[64:65], v[192:193], v[138:139] op_sel_hi:[1,0]
	v_pk_mul_f32 v[66:67], v[78:79], v[138:139] op_sel_hi:[1,0]
	s_waitcnt vmcnt(1)
	v_pk_mul_f32 v[64:65], v[64:65], v[68:69]
	v_bitop3_b32 v68, v216, v217, 30 bitop3:0x36
	v_pk_mul_f32 v[66:67], v[66:67], v[70:71]
	v_lshl_add_u32 v141, v68, 4, v219
	ds_write_b128 v141, v[64:67]
	v_lshl_add_u32 v64, v137, 9, s0
	v_xor_b32_e32 v65, v137, v215
	v_lshl_add_u32 v142, v65, 4, v64
	v_bitop3_b32 v65, v215, v137, 1 bitop3:0x36
	v_lshl_add_u32 v143, v65, 4, v64
	ds_read_b128 v[64:67], v142
	ds_read_b128 v[68:71], v143
	s_waitcnt vmcnt(0)
	v_lshlrev_b32_e32 v72, 16, v128
	v_and_b32_e32 v73, 0xffff0000, v128
	v_add_u32_e32 v74, s16, v144
	s_waitcnt lgkmcnt(1)
	v_pk_mul_f32 v[64:65], v[64:65], v[72:73]
	v_lshlrev_b32_e32 v72, 16, v129
	v_and_b32_e32 v73, 0xffff0000, v129
	v_pk_mul_f32 v[66:67], v[66:67], v[72:73]
	v_cvt_pk_bf16_f32 v64, v64, v65
	v_cvt_pk_bf16_f32 v65, v66, v67
	v_lshlrev_b32_e32 v66, 16, v130
	v_and_b32_e32 v67, 0xffff0000, v130
	s_waitcnt lgkmcnt(0)
	v_pk_mul_f32 v[66:67], v[68:69], v[66:67]
	v_lshlrev_b32_e32 v68, 16, v131
	v_and_b32_e32 v69, 0xffff0000, v131
	v_pk_mul_f32 v[68:69], v[70:71], v[68:69]
	v_cvt_pk_bf16_f32 v66, v66, v67
	v_cvt_pk_bf16_f32 v67, v68, v69
	v_lshlrev_b64 v[68:69], 12, v[134:135]
	v_lshl_add_u64 v[68:69], s[46:47], 0, v[68:69]
	v_lshl_add_u64 v[68:69], v[68:69], 0, s[42:43]
	v_lshl_add_u64 v[68:69], v[68:69], 0, v[222:223]
	global_store_dwordx4 v[68:69], v[64:67], off offset:2048
	v_bitop3_b32 v70, v137, v215, 4 bitop3:0x36
	v_ashrrev_i32_e32 v75, 31, v74
	v_mad_i64_i32 v[64:65], s[4:5], v74, s87, v[76:77]
	v_lshl_add_u64 v[64:65], v[64:65], 0, s[42:43]
	v_lshl_add_u64 v[64:65], v[64:65], 0, v[222:223]
	v_add_co_u32_e32 v64, vcc, s86, v64
	v_or_b32_e32 v153, 12, v137
	s_nop 0
	v_addc_co_u32_e32 v65, vcc, 0, v65, vcc
	v_or_b32_e32 v64, 1, v215
	v_lshl_add_u32 v65, v144, 9, s0
	v_lshl_add_u32 v145, v70, 4, v65
	v_bitop3_b32 v70, v137, v64, 4 bitop3:0x36
	v_lshl_add_u32 v146, v70, 4, v65
	ds_read_b128 v[70:73], v145
	ds_read_b128 v[78:81], v146
	v_lshl_add_u32 v65, v147, 9, s0
	v_or_b32_e32 v154, 16, v137
	v_or_b32_e32 v158, 20, v137
	v_or_b32_e32 v157, 24, v137
	v_or_b32_e32 v149, 28, v137
	v_mov_b32_e32 v66, v228
	v_mov_b32_e32 v67, v229
	v_mov_b32_e32 v68, v230
	v_mov_b32_e32 v69, v231
	s_add_u32 s6, s8, 0x3c000
	s_addc_u32 s7, s9, 0
	global_load_dwordx4 v[228:231], v244, s[6:7] offset:2048
	v_lshlrev_b32_e32 v82, 16, v66
	v_and_b32_e32 v83, 0xffff0000, v66
	s_waitcnt lgkmcnt(1)
	v_pk_mul_f32 v[70:71], v[70:71], v[82:83]
	s_nop 0
	v_cvt_pk_bf16_f32 v66, v70, v71
	v_lshlrev_b32_e32 v70, 16, v67
	v_and_b32_e32 v71, 0xffff0000, v67
	v_pk_mul_f32 v[70:71], v[72:73], v[70:71]
	s_nop 0
	v_cvt_pk_bf16_f32 v67, v70, v71
	v_lshlrev_b32_e32 v70, 16, v68
	v_and_b32_e32 v71, 0xffff0000, v68
	s_waitcnt lgkmcnt(0)
	v_pk_mul_f32 v[70:71], v[78:79], v[70:71]
	s_nop 0
	v_cvt_pk_bf16_f32 v68, v70, v71
	v_lshlrev_b32_e32 v70, 16, v69
	v_and_b32_e32 v71, 0xffff0000, v69
	v_pk_mul_f32 v[70:71], v[80:81], v[70:71]
	s_nop 0
	v_cvt_pk_bf16_f32 v69, v70, v71
	v_lshlrev_b64 v[70:71], 12, v[74:75]
	v_lshl_add_u64 v[70:71], s[46:47], 0, v[70:71]
	v_lshl_add_u64 v[70:71], v[70:71], 0, s[42:43]
	v_lshl_add_u64 v[70:71], v[70:71], 0, v[222:223]
	v_add_u32_e32 v74, s16, v147
	global_store_dwordx4 v[70:71], v[66:69], off offset:2048
	v_bitop3_b32 v70, v137, v215, 8 bitop3:0x36
	v_lshl_add_u32 v151, v70, 4, v65
	v_mad_i64_i32 v[66:67], s[4:5], v74, s87, v[76:77]
	v_lshl_add_u64 v[66:67], v[66:67], 0, s[42:43]
	v_lshl_add_u64 v[66:67], v[66:67], 0, v[222:223]
	v_add_co_u32_e32 v66, vcc, s86, v66
	v_bitop3_b32 v70, v137, v64, 8 bitop3:0x36
	s_nop 0
	v_addc_co_u32_e32 v67, vcc, 0, v67, vcc
	v_lshl_add_u32 v152, v70, 4, v65
	ds_read_b128 v[70:73], v151
	ds_read_b128 v[78:81], v152
	v_ashrrev_i32_e32 v75, 31, v74
	v_lshl_add_u32 v65, v153, 9, s0
	v_mov_b32_e32 v66, v232
	v_mov_b32_e32 v67, v233
	v_mov_b32_e32 v68, v234
	v_mov_b32_e32 v69, v235
	s_add_u32 s6, s8, 0x48000
	s_addc_u32 s7, s9, 0
	global_load_dwordx4 v[232:235], v244, s[6:7] offset:2048
	v_lshlrev_b32_e32 v82, 16, v66
	v_and_b32_e32 v83, 0xffff0000, v66
	s_waitcnt lgkmcnt(1)
; #define LAS __attribute__((address_space(3)))
; DI unsigned cvtpk(float lo, float hi) { f32x2 v = {lo, hi}; bf16x2_t b = __builtin_convertvector(v, bf16x2_t); return __builtin_bit_cast(unsigned, b); }
; DI void attn_unit(LAS unsigned char* lds, const bf16_t* P, bf16_t* Am, int qrow0, int h, int ntiles, int krow_ctx, int krow_lat,
;                   float lam, const float* subw, float outscale) {
;     ...
;             const int k16 = lane2 & 15;
; #pragma unroll
;             for (int i = 0; i < 8; ++i) { const int R = 4 * i + (lane2 >> 4);
;                 const f32x4 ta = *(const LAS f32x4*)(stg + R * 128 + (((2 * k16) ^ R) & 31) * 4), tb = *(const LAS f32x4*)(stg + R * 128 + (((2 * k16 + 1) ^ R) & 31) * 4);
;                 const size_t row = (size_t)(qrow0 + 64 * g + 32 * half + R);
;                 const u32x4 sg = *(const u32x4*)(P + row * DIN + O_AG + h * 128 + 8 * k16);
;                 u32x4 ov; ov.x = cvtpk(ta[0] * bf_lo(sg.x), ta[1] * bf_hi(sg.x)); ov.y = cvtpk(ta[2] * bf_lo(sg.y), ta[3] * bf_hi(sg.y));
;                 ov.z = cvtpk(tb[0] * bf_lo(sg.z), tb[1] * bf_hi(sg.z)); ov.w = cvtpk(tb[2] * bf_lo(sg.w), tb[3] * bf_hi(sg.w));
;                 *(u32x4*)(Am + row * DM + 1024 + h * 128 + 8 * k16) = ov; }
	v_pk_mul_f32 v[70:71], v[70:71], v[82:83]
	s_nop 0
	v_cvt_pk_bf16_f32 v66, v70, v71
	v_lshlrev_b32_e32 v70, 16, v67
	v_and_b32_e32 v71, 0xffff0000, v67
	v_pk_mul_f32 v[70:71], v[72:73], v[70:71]
	s_nop 0
	v_cvt_pk_bf16_f32 v67, v70, v71
	v_lshlrev_b32_e32 v70, 16, v68
	v_and_b32_e32 v71, 0xffff0000, v68
	s_waitcnt lgkmcnt(0)
	v_pk_mul_f32 v[70:71], v[78:79], v[70:71]
	s_nop 0
	v_cvt_pk_bf16_f32 v68, v70, v71
	v_lshlrev_b32_e32 v70, 16, v69
	v_and_b32_e32 v71, 0xffff0000, v69
	v_pk_mul_f32 v[70:71], v[80:81], v[70:71]
	s_nop 0
	v_cvt_pk_bf16_f32 v69, v70, v71
	v_lshlrev_b64 v[70:71], 12, v[74:75]
	v_lshl_add_u64 v[70:71], s[46:47], 0, v[70:71]
	v_lshl_add_u64 v[70:71], v[70:71], 0, s[42:43]
	v_lshl_add_u64 v[70:71], v[70:71], 0, v[222:223]
	v_add_u32_e32 v74, s16, v153
	global_store_dwordx4 v[70:71], v[66:69], off offset:2048
	v_bitop3_b32 v70, v137, v215, 12 bitop3:0x36
	v_lshl_add_u32 v155, v70, 4, v65
	v_mad_i64_i32 v[66:67], s[4:5], v74, s87, v[76:77]
	v_lshl_add_u64 v[66:67], v[66:67], 0, s[42:43]
	v_lshl_add_u64 v[66:67], v[66:67], 0, v[222:223]
	v_add_co_u32_e32 v66, vcc, s86, v66
	v_bitop3_b32 v70, v137, v64, 12 bitop3:0x36
	s_nop 0
	v_addc_co_u32_e32 v67, vcc, 0, v67, vcc
	v_lshl_add_u32 v156, v70, 4, v65
	ds_read_b128 v[70:73], v155
	ds_read_b128 v[78:81], v156
	v_ashrrev_i32_e32 v75, 31, v74
	v_lshl_add_u32 v65, v154, 9, s0
	v_mov_b32_e32 v66, v236
	v_mov_b32_e32 v67, v237
	v_mov_b32_e32 v68, v238
	v_mov_b32_e32 v69, v239
	s_add_u32 s6, s8, 0x54000
	s_addc_u32 s7, s9, 0
	global_load_dwordx4 v[236:239], v244, s[6:7] offset:2048
	v_lshlrev_b32_e32 v82, 16, v66
	v_and_b32_e32 v83, 0xffff0000, v66
	s_waitcnt lgkmcnt(1)
	v_pk_mul_f32 v[70:71], v[70:71], v[82:83]
	s_nop 0
	v_cvt_pk_bf16_f32 v66, v70, v71
	v_lshlrev_b32_e32 v70, 16, v67
	v_and_b32_e32 v71, 0xffff0000, v67
	v_pk_mul_f32 v[70:71], v[72:73], v[70:71]
	s_nop 0
	v_cvt_pk_bf16_f32 v67, v70, v71
	v_lshlrev_b32_e32 v70, 16, v68
	v_and_b32_e32 v71, 0xffff0000, v68
	s_waitcnt lgkmcnt(0)
	v_pk_mul_f32 v[70:71], v[78:79], v[70:71]
	s_nop 0
	v_cvt_pk_bf16_f32 v68, v70, v71
	v_lshlrev_b32_e32 v70, 16, v69
	v_and_b32_e32 v71, 0xffff0000, v69
	v_pk_mul_f32 v[70:71], v[80:81], v[70:71]
	s_nop 0
	v_cvt_pk_bf16_f32 v69, v70, v71
	v_lshlrev_b64 v[70:71], 12, v[74:75]
	v_lshl_add_u64 v[70:71], s[46:47], 0, v[70:71]
	v_lshl_add_u64 v[70:71], v[70:71], 0, s[42:43]
	v_lshl_add_u64 v[70:71], v[70:71], 0, v[222:223]
	v_add_u32_e32 v74, s16, v154
	global_store_dwordx4 v[70:71], v[66:69], off offset:2048
	v_bitop3_b32 v70, v137, v215, 16 bitop3:0x36
	v_lshl_add_u32 v138, v70, 4, v65
	v_mad_i64_i32 v[66:67], s[4:5], v74, s87, v[76:77]
	v_lshl_add_u64 v[66:67], v[66:67], 0, s[42:43]
	v_lshl_add_u64 v[66:67], v[66:67], 0, v[222:223]
	v_add_co_u32_e32 v66, vcc, s86, v66
	v_bitop3_b32 v70, v137, v64, 16 bitop3:0x36
	s_nop 0
	v_addc_co_u32_e32 v67, vcc, 0, v67, vcc
	v_lshl_add_u32 v140, v70, 4, v65
	ds_read_b128 v[70:73], v138
	ds_read_b128 v[78:81], v140
	v_ashrrev_i32_e32 v75, 31, v74
	v_lshl_add_u32 v65, v158, 9, s0
	v_mov_b32_e32 v66, v240
	v_mov_b32_e32 v67, v241
	v_mov_b32_e32 v68, v242
	v_mov_b32_e32 v69, v243
	v_lshlrev_b32_e32 v82, 16, v66
	v_and_b32_e32 v83, 0xffff0000, v66
	s_waitcnt lgkmcnt(1)
	v_pk_mul_f32 v[70:71], v[70:71], v[82:83]
	s_nop 0
	v_cvt_pk_bf16_f32 v66, v70, v71
	v_lshlrev_b32_e32 v70, 16, v67
	v_and_b32_e32 v71, 0xffff0000, v67
	v_pk_mul_f32 v[70:71], v[72:73], v[70:71]
	s_nop 0
	v_cvt_pk_bf16_f32 v67, v70, v71
	v_lshlrev_b32_e32 v70, 16, v68
	v_and_b32_e32 v71, 0xffff0000, v68
	s_waitcnt lgkmcnt(0)
	v_pk_mul_f32 v[70:71], v[78:79], v[70:71]
	s_nop 0
	v_cvt_pk_bf16_f32 v68, v70, v71
	v_lshlrev_b32_e32 v70, 16, v69
	v_and_b32_e32 v71, 0xffff0000, v69
	v_pk_mul_f32 v[70:71], v[80:81], v[70:71]
	s_nop 0
	v_cvt_pk_bf16_f32 v69, v70, v71
	v_lshlrev_b64 v[70:71], 12, v[74:75]
	v_lshl_add_u64 v[70:71], s[46:47], 0, v[70:71]
	v_lshl_add_u64 v[70:71], v[70:71], 0, s[42:43]
	v_lshl_add_u64 v[70:71], v[70:71], 0, v[222:223]
	v_add_u32_e32 v74, s16, v158
	global_store_dwordx4 v[70:71], v[66:69], off offset:2048
	v_bitop3_b32 v70, v137, v215, 20 bitop3:0x36
	v_lshl_add_u32 v134, v70, 4, v65
	v_mad_i64_i32 v[66:67], s[4:5], v74, s87, v[76:77]
	v_lshl_add_u64 v[66:67], v[66:67], 0, s[42:43]
	v_lshl_add_u64 v[66:67], v[66:67], 0, v[222:223]
	v_add_co_u32_e32 v66, vcc, s86, v66
	v_bitop3_b32 v70, v137, v64, 20 bitop3:0x36
	s_nop 0
	v_addc_co_u32_e32 v67, vcc, 0, v67, vcc
	v_lshl_add_u32 v135, v70, 4, v65
	ds_read_b128 v[70:73], v134
	ds_read_b128 v[78:81], v135
	v_ashrrev_i32_e32 v75, 31, v74
	v_lshl_add_u32 v65, v157, 9, s0
	s_waitcnt vmcnt(6)
	v_mov_b32_e32 v66, v228
	v_mov_b32_e32 v67, v229
	v_mov_b32_e32 v68, v230
	v_mov_b32_e32 v69, v231
	v_lshlrev_b32_e32 v82, 16, v66
	v_and_b32_e32 v83, 0xffff0000, v66
	s_waitcnt lgkmcnt(1)
	v_pk_mul_f32 v[70:71], v[70:71], v[82:83]
	s_nop 0
	v_cvt_pk_bf16_f32 v66, v70, v71
	v_lshlrev_b32_e32 v70, 16, v67
	v_and_b32_e32 v71, 0xffff0000, v67
	v_pk_mul_f32 v[70:71], v[72:73], v[70:71]
	s_nop 0
	v_cvt_pk_bf16_f32 v67, v70, v71
	v_lshlrev_b32_e32 v70, 16, v68
	v_and_b32_e32 v71, 0xffff0000, v68
	s_waitcnt lgkmcnt(0)
; #define LAS __attribute__((address_space(3)))
; DI unsigned cvtpk(float lo, float hi) { f32x2 v = {lo, hi}; bf16x2_t b = __builtin_convertvector(v, bf16x2_t); return __builtin_bit_cast(unsigned, b); }
; DI void attn_unit(LAS unsigned char* lds, const bf16_t* P, bf16_t* Am, int qrow0, int h, int ntiles, int krow_ctx, int krow_lat,
;                   float lam, const float* subw, float outscale) {
;     ...
;             float ss = 0.f; const float inv = half ? invb : inva;
; #pragma unroll
;             for (int d0 = 0; d0 < 4; ++d0)
; #pragma unroll
;                 for (int r = 0; r < 16; ++r) { const float v = (half ? ob[d0][r] : oa[d0][r]) * inv - xch[half * 4096 + (d0 * 16 + r) * 64 + lane2]; if (half) ob[d0][r] = v; else oa[d0][r] = v; ss += v * v; }
;             ss = sum_x32(ss);
;     ...
;             const int k16 = lane2 & 15;
; #pragma unroll
;             for (int i = 0; i < 8; ++i) { const int R = 4 * i + (lane2 >> 4);
;                 const f32x4 ta = *(const LAS f32x4*)(stg + R * 128 + (((2 * k16) ^ R) & 31) * 4), tb = *(const LAS f32x4*)(stg + R * 128 + (((2 * k16 + 1) ^ R) & 31) * 4);
;                 const size_t row = (size_t)(qrow0 + 64 * g + 32 * half + R);
;                 const u32x4 sg = *(const u32x4*)(P + row * DIN + O_AG + h * 128 + 8 * k16);
;                 u32x4 ov; ov.x = cvtpk(ta[0] * bf_lo(sg.x), ta[1] * bf_hi(sg.x)); ov.y = cvtpk(ta[2] * bf_lo(sg.y), ta[3] * bf_hi(sg.y));
;                 ov.z = cvtpk(tb[0] * bf_lo(sg.z), tb[1] * bf_hi(sg.z)); ov.w = cvtpk(tb[2] * bf_lo(sg.w), tb[3] * bf_hi(sg.w));
;                 *(u32x4*)(Am + row * DM + 1024 + h * 128 + 8 * k16) = ov; }
	v_pk_mul_f32 v[70:71], v[78:79], v[70:71]
	s_nop 0
	v_cvt_pk_bf16_f32 v68, v70, v71
	v_lshlrev_b32_e32 v70, 16, v69
	v_and_b32_e32 v71, 0xffff0000, v69
	v_pk_mul_f32 v[70:71], v[80:81], v[70:71]
	s_nop 0
	v_cvt_pk_bf16_f32 v69, v70, v71
	v_lshlrev_b64 v[70:71], 12, v[74:75]
	v_lshl_add_u64 v[70:71], s[46:47], 0, v[70:71]
	v_lshl_add_u64 v[70:71], v[70:71], 0, s[42:43]
	v_lshl_add_u64 v[70:71], v[70:71], 0, v[222:223]
	global_store_dwordx4 v[70:71], v[66:69], off offset:2048
	v_add_u32_e32 v70, s16, v157
	v_bitop3_b32 v71, v137, v215, 24 bitop3:0x36
	v_mad_i64_i32 v[66:67], s[4:5], v70, s87, v[76:77]
	v_lshl_add_u64 v[66:67], v[66:67], 0, s[42:43]
	v_lshl_add_u64 v[66:67], v[66:67], 0, v[222:223]
	v_add_co_u32_e32 v66, vcc, s86, v66
	v_lshl_add_u32 v148, v71, 4, v65
	s_nop 0
	v_addc_co_u32_e32 v67, vcc, 0, v67, vcc
	v_ashrrev_i32_e32 v71, 31, v70
	v_add_u32_e32 v74, s16, v149
	v_lshlrev_b64 v[70:71], 12, v[70:71]
	v_mad_i64_i32 v[72:73], s[4:5], v74, s87, v[76:77]
	v_lshl_add_u64 v[70:71], s[46:47], 0, v[70:71]
	v_bitop3_b32 v75, v137, v64, 24 bitop3:0x36
	v_lshl_add_u64 v[72:73], v[72:73], 0, s[42:43]
	v_lshl_add_u64 v[70:71], v[70:71], 0, s[42:43]
	v_lshl_add_u32 v150, v75, 4, v65
	v_lshl_add_u64 v[82:83], v[72:73], 0, v[222:223]
	v_lshl_add_u64 v[84:85], v[70:71], 0, v[222:223]
	ds_read_b128 v[70:73], v148
	ds_read_b128 v[78:81], v150
	v_lshl_add_u32 v65, v149, 9, s0
	v_bitop3_b32 v75, v137, v215, 28 bitop3:0x36
	v_lshl_add_u32 v159, v75, 4, v65
	v_bitop3_b32 v64, v137, v64, 28 bitop3:0x36
	v_ashrrev_i32_e32 v75, 31, v74
	v_lshl_add_u32 v160, v64, 4, v65
	v_lshlrev_b64 v[64:65], 12, v[74:75]
	v_lshl_add_u64 v[64:65], s[46:47], 0, v[64:65]
	s_add_i32 s16, s16, 32
	s_waitcnt vmcnt(5)
	v_mov_b32_e32 v66, v232
	v_mov_b32_e32 v67, v233
	v_mov_b32_e32 v68, v234
	v_mov_b32_e32 v69, v235
	v_lshlrev_b32_e32 v86, 16, v66
	v_and_b32_e32 v87, 0xffff0000, v66
	v_lshlrev_b32_e32 v66, 16, v67
	v_and_b32_e32 v67, 0xffff0000, v67
	v_lshlrev_b32_e32 v88, 16, v68
	v_and_b32_e32 v89, 0xffff0000, v68
	v_lshlrev_b32_e32 v68, 16, v69
	v_and_b32_e32 v69, 0xffff0000, v69
	s_waitcnt lgkmcnt(1)
	v_pk_mul_f32 v[70:71], v[70:71], v[86:87]
	v_pk_mul_f32 v[72:73], v[72:73], v[66:67]
	s_waitcnt lgkmcnt(0)
	v_pk_mul_f32 v[78:79], v[78:79], v[88:89]
	v_pk_mul_f32 v[80:81], v[80:81], v[68:69]
	v_cvt_pk_bf16_f32 v66, v70, v71
	v_cvt_pk_bf16_f32 v67, v72, v73
	v_cvt_pk_bf16_f32 v68, v78, v79
	v_cvt_pk_bf16_f32 v69, v80, v81
	global_store_dwordx4 v[84:85], v[66:69], off offset:2048
	s_nop 1
	v_add_co_u32_e32 v66, vcc, s86, v82
	s_nop 1
	v_addc_co_u32_e32 v67, vcc, 0, v83, vcc
	ds_read2st64_b32 v[66:67], v214 offset0:64 offset1:65
	ds_read2st64_b32 v[68:69], v214 offset0:66 offset1:67
	ds_read2st64_b32 v[70:71], v214 offset0:68 offset1:69
	ds_read2st64_b32 v[72:73], v214 offset0:70 offset1:71
	ds_read2st64_b32 v[82:83], v214 offset0:72 offset1:73
	ds_read2st64_b32 v[84:85], v214 offset0:74 offset1:75
	ds_read2st64_b32 v[86:87], v214 offset0:76 offset1:77
	ds_read2st64_b32 v[88:89], v214 offset0:78 offset1:79
	ds_read2st64_b32 v[90:91], v214 offset0:80 offset1:81
	ds_read2st64_b32 v[92:93], v214 offset0:82 offset1:83
	ds_read2st64_b32 v[94:95], v214 offset0:84 offset1:85
	ds_read2st64_b32 v[96:97], v214 offset0:86 offset1:87
	ds_read2st64_b32 v[98:99], v214 offset0:88 offset1:89
	ds_read2st64_b32 v[100:101], v214 offset0:90 offset1:91
	ds_read2st64_b32 v[162:163], v214 offset0:92 offset1:93
	ds_read2st64_b32 v[164:165], v214 offset0:94 offset1:95
	ds_read2st64_b32 v[166:167], v214 offset0:96 offset1:97
	ds_read2st64_b32 v[168:169], v214 offset0:98 offset1:99
	ds_read2st64_b32 v[102:103], v214 offset0:100 offset1:101
	ds_read2st64_b32 v[104:105], v214 offset0:102 offset1:103
	ds_read2st64_b32 v[106:107], v214 offset0:104 offset1:105
	ds_read2st64_b32 v[108:109], v214 offset0:106 offset1:107
	ds_read2st64_b32 v[132:133], v214 offset0:108 offset1:109
	ds_read2st64_b32 v[130:131], v214 offset0:110 offset1:111
	ds_read2st64_b32 v[116:117], v214 offset0:112 offset1:113
	ds_read2st64_b32 v[122:123], v214 offset0:114 offset1:115
	ds_read2st64_b32 v[126:127], v214 offset0:116 offset1:117
	ds_read2st64_b32 v[128:129], v214 offset0:118 offset1:119
	ds_read2st64_b32 v[124:125], v214 offset0:120 offset1:121
	ds_read2st64_b32 v[120:121], v214 offset0:122 offset1:123
	ds_read2st64_b32 v[118:119], v214 offset0:124 offset1:125
	ds_read2st64_b32 v[114:115], v214 offset0:126 offset1:127
	s_waitcnt lgkmcnt(14)
	v_pk_fma_f32 v[110:111], v[48:49], v[136:137], v[66:67] op_sel_hi:[1,0,1] neg_lo:[0,0,1] neg_hi:[0,0,1]
	v_pk_fma_f32 v[112:113], v[50:51], v[136:137], v[68:69] op_sel_hi:[1,0,1] neg_lo:[0,0,1] neg_hi:[0,0,1]
	v_lshl_add_u64 v[48:49], v[64:65], 0, s[42:43]
	v_mul_f32_e32 v50, v111, v111
	v_lshl_add_u64 v[64:65], v[48:49], 0, v[222:223]
	v_pk_fma_f32 v[48:49], v[110:111], v[110:111], v[50:51] op_sel_hi:[1,1,0]
	v_pk_fma_f32 v[68:69], v[52:53], v[136:137], v[70:71] op_sel_hi:[1,0,1] neg_lo:[0,0,1] neg_hi:[0,0,1]
	v_mul_f32_e32 v52, v113, v113
	v_pk_fma_f32 v[48:49], v[112:113], v[112:113], v[48:49]
	v_pk_fma_f32 v[70:71], v[54:55], v[136:137], v[72:73] op_sel_hi:[1,0,1] neg_lo:[0,0,1] neg_hi:[0,0,1]
	v_pk_add_f32 v[48:49], v[48:49], v[52:53] op_sel_hi:[1,0]
	v_mul_f32_e32 v54, v69, v69
	v_pk_fma_f32 v[48:49], v[68:69], v[68:69], v[48:49]
	v_pk_fma_f32 v[72:73], v[56:57], v[136:137], v[82:83] op_sel_hi:[1,0,1] neg_lo:[0,0,1] neg_hi:[0,0,1]
	v_pk_add_f32 v[48:49], v[48:49], v[54:55] op_sel_hi:[1,0]
	v_mul_f32_e32 v56, v71, v71
	v_pk_fma_f32 v[48:49], v[70:71], v[70:71], v[48:49]
	v_mul_f32_e32 v74, v73, v73
	v_pk_add_f32 v[48:49], v[48:49], v[56:57] op_sel_hi:[1,0]
	s_waitcnt lgkmcnt(13)
; #define LAS __attribute__((address_space(3)))
; DI unsigned cvtpk(float lo, float hi) { f32x2 v = {lo, hi}; bf16x2_t b = __builtin_convertvector(v, bf16x2_t); return __builtin_bit_cast(unsigned, b); }
; DI void attn_unit(LAS unsigned char* lds, const bf16_t* P, bf16_t* Am, int qrow0, int h, int ntiles, int krow_ctx, int krow_lat,
;                   float lam, const float* subw, float outscale) {
;     ...
;                 for (int r = 0; r < 16; ++r) { const float v = (half ? ob[d0][r] : oa[d0][r]) * inv - xch[half * 4096 + (d0 * 16 + r) * 64 + lane2]; if (half) ob[d0][r] = v; else oa[d0][r] = v; ss += v * v; }
;             ss = sum_x32(ss);
;             const float rr = rsqrtf(ss * (1.0f / 128.0f) + EPS) * outscale;
;             LAS float* stg = xch + half * 4096;
; #pragma unroll
;             for (int d0 = 0; d0 < 4; ++d0)
; #pragma unroll
;                 for (int rg = 0; rg < 4; ++rg) { const int e0 = 32 * d0 + 8 * rg, cc = 8 * d0 + 2 * rg + hie;
;                     const f32x4 w4 = *(const f32x4*)(subw + e0 + 4 * hie);
;                     const float v0 = half ? ob[d0][4 * rg + 0] : oa[d0][4 * rg + 0], v1 = half ? ob[d0][4 * rg + 1] : oa[d0][4 * rg + 1];
;                     const float v2 = half ? ob[d0][4 * rg + 2] : oa[d0][4 * rg + 2], v3 = half ? ob[d0][4 * rg + 3] : oa[d0][4 * rg + 3];
;                     const f32x4 tv = {v0 * rr * w4[0], v1 * rr * w4[1], v2 * rr * w4[2], v3 * rr * w4[3]};
;                     *(LAS f32x4*)(stg + r32e * 128 + ((cc ^ r32e) & 31) * 4) = tv; }
;             const int k16 = lane2 & 15;
; #pragma unroll
;             for (int i = 0; i < 8; ++i) { const int R = 4 * i + (lane2 >> 4);
;                 const f32x4 ta = *(const LAS f32x4*)(stg + R * 128 + (((2 * k16) ^ R) & 31) * 4), tb = *(const LAS f32x4*)(stg + R * 128 + (((2 * k16 + 1) ^ R) & 31) * 4);
;                 const size_t row = (size_t)(qrow0 + 64 * g + 32 * half + R);
;                 const u32x4 sg = *(const u32x4*)(P + row * DIN + O_AG + h * 128 + 8 * k16);
;                 u32x4 ov; ov.x = cvtpk(ta[0] * bf_lo(sg.x), ta[1] * bf_hi(sg.x)); ov.y = cvtpk(ta[2] * bf_lo(sg.y), ta[3] * bf_hi(sg.y));
;                 ov.z = cvtpk(tb[0] * bf_lo(sg.z), tb[1] * bf_hi(sg.z)); ov.w = cvtpk(tb[2] * bf_lo(sg.w), tb[3] * bf_hi(sg.w));
;                 *(u32x4*)(Am + row * DM + 1024 + h * 128 + 8 * k16) = ov; }
	v_pk_fma_f32 v[102:103], v[20:21], v[136:137], v[102:103] op_sel_hi:[1,0,1] neg_lo:[0,0,1] neg_hi:[0,0,1]
	v_pk_fma_f32 v[56:57], v[72:73], v[72:73], v[48:49]
	ds_read_b128 v[48:51], v159
	ds_read_b128 v[52:55], v160
	s_waitcnt lgkmcnt(14)
	v_pk_fma_f32 v[104:105], v[22:23], v[136:137], v[104:105] op_sel_hi:[1,0,1] neg_lo:[0,0,1] neg_hi:[0,0,1]
	s_waitcnt lgkmcnt(13)
	v_pk_fma_f32 v[106:107], v[24:25], v[136:137], v[106:107] op_sel_hi:[1,0,1] neg_lo:[0,0,1] neg_hi:[0,0,1]
	v_mul_f32_e32 v22, v105, v105
	s_waitcnt lgkmcnt(12)
	v_pk_fma_f32 v[108:109], v[26:27], v[136:137], v[108:109] op_sel_hi:[1,0,1] neg_lo:[0,0,1] neg_hi:[0,0,1]
	s_waitcnt lgkmcnt(11)
	v_pk_fma_f32 v[28:29], v[28:29], v[136:137], v[132:133] op_sel_hi:[1,0,1] neg_lo:[0,0,1] neg_hi:[0,0,1]
	s_waitcnt lgkmcnt(10)
	v_pk_fma_f32 v[30:31], v[30:31], v[136:137], v[130:131] op_sel_hi:[1,0,1] neg_lo:[0,0,1] neg_hi:[0,0,1]
	s_waitcnt lgkmcnt(9)
	v_pk_fma_f32 v[116:117], v[0:1], v[136:137], v[116:117] op_sel_hi:[1,0,1] neg_lo:[0,0,1] neg_hi:[0,0,1]
	s_waitcnt lgkmcnt(8)
	v_pk_fma_f32 v[122:123], v[2:3], v[136:137], v[122:123] op_sel_hi:[1,0,1] neg_lo:[0,0,1] neg_hi:[0,0,1]
	s_waitcnt lgkmcnt(7)
	v_pk_fma_f32 v[126:127], v[4:5], v[136:137], v[126:127] op_sel_hi:[1,0,1] neg_lo:[0,0,1] neg_hi:[0,0,1]
	v_mul_f32_e32 v2, v123, v123
	s_waitcnt lgkmcnt(6)
	v_pk_fma_f32 v[128:129], v[6:7], v[136:137], v[128:129] op_sel_hi:[1,0,1] neg_lo:[0,0,1] neg_hi:[0,0,1]
	s_waitcnt lgkmcnt(5)
	v_pk_fma_f32 v[124:125], v[8:9], v[136:137], v[124:125] op_sel_hi:[1,0,1] neg_lo:[0,0,1] neg_hi:[0,0,1]
	s_waitcnt lgkmcnt(4)
	v_pk_fma_f32 v[120:121], v[10:11], v[136:137], v[120:121] op_sel_hi:[1,0,1] neg_lo:[0,0,1] neg_hi:[0,0,1]
	s_waitcnt lgkmcnt(3)
	v_pk_fma_f32 v[118:119], v[12:13], v[136:137], v[118:119] op_sel_hi:[1,0,1] neg_lo:[0,0,1] neg_hi:[0,0,1]
	s_waitcnt lgkmcnt(2)
	v_pk_fma_f32 v[114:115], v[14:15], v[136:137], v[114:115] op_sel_hi:[1,0,1] neg_lo:[0,0,1] neg_hi:[0,0,1]
	s_waitcnt vmcnt(4)
	v_mov_b32_e32 v78, v236
	v_mov_b32_e32 v79, v237
	v_mov_b32_e32 v80, v238
	v_mov_b32_e32 v81, v239
	v_lshlrev_b32_e32 v66, 16, v78
	v_and_b32_e32 v67, 0xffff0000, v78
	v_lshlrev_b32_e32 v78, 16, v79
	v_and_b32_e32 v79, 0xffff0000, v79
	v_lshlrev_b32_e32 v82, 16, v80
	v_and_b32_e32 v83, 0xffff0000, v80
	v_lshlrev_b32_e32 v80, 16, v81
	v_and_b32_e32 v81, 0xffff0000, v81
	s_waitcnt lgkmcnt(1)
	v_pk_mul_f32 v[48:49], v[48:49], v[66:67]
	v_pk_mul_f32 v[50:51], v[50:51], v[78:79]
	s_waitcnt lgkmcnt(0)
	v_pk_mul_f32 v[52:53], v[52:53], v[82:83]
	v_pk_mul_f32 v[54:55], v[54:55], v[80:81]
	v_cvt_pk_bf16_f32 v48, v48, v49
	v_cvt_pk_bf16_f32 v49, v50, v51
	v_cvt_pk_bf16_f32 v50, v52, v53
	v_cvt_pk_bf16_f32 v51, v54, v55
	global_store_dwordx4 v[64:65], v[48:51], off offset:2048
	s_add_u32 s6, s8, 0x6c000
	s_addc_u32 s7, s9, 0
	global_load_dwordx4 v[228:231], v244, s[6:7] offset:2048
	s_add_u32 s6, s8, 0x78000
	s_addc_u32 s7, s9, 0
	global_load_dwordx4 v[232:235], v244, s[6:7] offset:2048
	s_add_u32 s6, s8, 0x84000
	s_addc_u32 s7, s9, 0
	global_load_dwordx4 v[236:239], v244, s[6:7] offset:2048
	s_add_u32 s6, s8, 0x90000
	s_addc_u32 s7, s9, 0
	global_load_dwordx4 v[240:243], v244, s[6:7] offset:2048
	global_load_dwordx4 v[64:67], v204, s[36:37]
	s_nop 0
	global_load_dwordx4 v[48:51], v204, s[36:37] offset:32
	v_pk_add_f32 v[52:53], v[56:57], v[74:75] op_sel_hi:[1,0]
	v_pk_fma_f32 v[74:75], v[58:59], v[136:137], v[84:85] op_sel_hi:[1,0,1] neg_lo:[0,0,1] neg_hi:[0,0,1]
	v_pk_fma_f32 v[78:79], v[60:61], v[136:137], v[86:87] op_sel_hi:[1,0,1] neg_lo:[0,0,1] neg_hi:[0,0,1]
	v_pk_fma_f32 v[52:53], v[74:75], v[74:75], v[52:53]
	v_mul_f32_e32 v54, v75, v75
	v_pk_add_f32 v[80:81], v[52:53], v[54:55] op_sel_hi:[1,0]
	v_pk_fma_f32 v[82:83], v[32:33], v[136:137], v[90:91] op_sel_hi:[1,0,1] neg_lo:[0,0,1] neg_hi:[0,0,1]
	v_pk_fma_f32 v[60:61], v[78:79], v[78:79], v[80:81]
	v_mul_f32_e32 v80, v79, v79
	v_pk_add_f32 v[60:61], v[60:61], v[80:81] op_sel_hi:[1,0]
	v_pk_fma_f32 v[80:81], v[62:63], v[136:137], v[88:89] op_sel_hi:[1,0,1] neg_lo:[0,0,1] neg_hi:[0,0,1]
	v_pk_fma_f32 v[84:85], v[34:35], v[136:137], v[92:93] op_sel_hi:[1,0,1] neg_lo:[0,0,1] neg_hi:[0,0,1]
	v_pk_fma_f32 v[60:61], v[80:81], v[80:81], v[60:61]
	v_mul_f32_e32 v62, v81, v81
	v_pk_add_f32 v[60:61], v[60:61], v[62:63] op_sel_hi:[1,0]
	v_mul_f32_e32 v34, v85, v85
	v_pk_fma_f32 v[32:33], v[82:83], v[82:83], v[60:61]
	v_mul_f32_e32 v60, v83, v83
	v_pk_add_f32 v[32:33], v[32:33], v[60:61] op_sel_hi:[1,0]
	v_pk_fma_f32 v[86:87], v[36:37], v[136:137], v[94:95] op_sel_hi:[1,0,1] neg_lo:[0,0,1] neg_hi:[0,0,1]
	v_pk_fma_f32 v[32:33], v[84:85], v[84:85], v[32:33]
	v_pk_fma_f32 v[90:91], v[40:41], v[136:137], v[98:99] op_sel_hi:[1,0,1] neg_lo:[0,0,1] neg_hi:[0,0,1]
	v_pk_add_f32 v[88:89], v[32:33], v[34:35] op_sel_hi:[1,0]
	v_pk_fma_f32 v[92:93], v[42:43], v[136:137], v[100:101] op_sel_hi:[1,0,1] neg_lo:[0,0,1] neg_hi:[0,0,1]
	v_pk_fma_f32 v[36:37], v[86:87], v[86:87], v[88:89]
	v_mul_f32_e32 v88, v87, v87
	v_pk_add_f32 v[36:37], v[36:37], v[88:89] op_sel_hi:[1,0]
	v_pk_fma_f32 v[88:89], v[38:39], v[136:137], v[96:97] op_sel_hi:[1,0,1] neg_lo:[0,0,1] neg_hi:[0,0,1]
	v_pk_fma_f32 v[94:95], v[44:45], v[136:137], v[162:163] op_sel_hi:[1,0,1] neg_lo:[0,0,1] neg_hi:[0,0,1]
	v_pk_fma_f32 v[36:37], v[88:89], v[88:89], v[36:37]
	v_mul_f32_e32 v38, v89, v89
	v_pk_add_f32 v[36:37], v[36:37], v[38:39] op_sel_hi:[1,0]
	v_mul_f32_e32 v38, v91, v91
	v_pk_fma_f32 v[36:37], v[90:91], v[90:91], v[36:37]
	v_pk_fma_f32 v[98:99], v[16:17], v[136:137], v[166:167] op_sel_hi:[1,0,1] neg_lo:[0,0,1] neg_hi:[0,0,1]
	v_pk_add_f32 v[36:37], v[36:37], v[38:39] op_sel_hi:[1,0]
	v_mul_f32_e32 v38, v93, v93
; #define LAS __attribute__((address_space(3)))
; DI void attn_unit(LAS unsigned char* lds, const bf16_t* P, bf16_t* Am, int qrow0, int h, int ntiles, int krow_ctx, int krow_lat,
;                   float lam, const float* subw, float outscale) {
;     ...
;                 for (int r = 0; r < 16; ++r) { const float v = (half ? ob[d0][r] : oa[d0][r]) * inv - xch[half * 4096 + (d0 * 16 + r) * 64 + lane2]; if (half) ob[d0][r] = v; else oa[d0][r] = v; ss += v * v; }
;             ss = sum_x32(ss);
;             const float rr = rsqrtf(ss * (1.0f / 128.0f) + EPS) * outscale;
;             LAS float* stg = xch + half * 4096;
; #pragma unroll
;             for (int d0 = 0; d0 < 4; ++d0)
; #pragma unroll
;                 for (int rg = 0; rg < 4; ++rg) { const int e0 = 32 * d0 + 8 * rg, cc = 8 * d0 + 2 * rg + hie;
;                     const f32x4 w4 = *(const f32x4*)(subw + e0 + 4 * hie);
;                     const float v0 = half ? ob[d0][4 * rg + 0] : oa[d0][4 * rg + 0], v1 = half ? ob[d0][4 * rg + 1] : oa[d0][4 * rg + 1];
;                     const float v2 = half ? ob[d0][4 * rg + 2] : oa[d0][4 * rg + 2], v3 = half ? ob[d0][4 * rg + 3] : oa[d0][4 * rg + 3];
;                     const f32x4 tv = {v0 * rr * w4[0], v1 * rr * w4[1], v2 * rr * w4[2], v3 * rr * w4[3]};
;                     *(LAS f32x4*)(stg + r32e * 128 + ((cc ^ r32e) & 31) * 4) = tv; }
;             const int k16 = lane2 & 15;
; #pragma unroll
;             for (int i = 0; i < 8; ++i) { const int R = 4 * i + (lane2 >> 4);
;                 const f32x4 ta = *(const LAS f32x4*)(stg + R * 128 + (((2 * k16) ^ R) & 31) * 4), tb = *(const LAS f32x4*)(stg + R * 128 + (((2 * k16 + 1) ^ R) & 31) * 4);
;                 const size_t row = (size_t)(qrow0 + 64 * g + 32 * half + R);
;                 const u32x4 sg = *(const u32x4*)(P + row * DIN + O_AG + h * 128 + 8 * k16);
	v_pk_fma_f32 v[36:37], v[92:93], v[92:93], v[36:37]
	v_pk_fma_f32 v[100:101], v[18:19], v[136:137], v[168:169] op_sel_hi:[1,0,1] neg_lo:[0,0,1] neg_hi:[0,0,1]
	v_pk_add_f32 v[96:97], v[36:37], v[38:39] op_sel_hi:[1,0]
	v_mul_f32_e32 v18, v101, v101
	v_pk_fma_f32 v[44:45], v[94:95], v[94:95], v[96:97]
	v_mul_f32_e32 v96, v95, v95
	v_pk_add_f32 v[44:45], v[44:45], v[96:97] op_sel_hi:[1,0]
	v_pk_fma_f32 v[96:97], v[46:47], v[136:137], v[164:165] op_sel_hi:[1,0,1] neg_lo:[0,0,1] neg_hi:[0,0,1]
	global_load_dwordx4 v[56:59], v204, s[36:37] offset:64
	global_load_dwordx4 v[52:55], v204, s[36:37] offset:96
	v_pk_fma_f32 v[44:45], v[96:97], v[96:97], v[44:45]
	v_mul_f32_e32 v46, v97, v97
	v_pk_add_f32 v[44:45], v[44:45], v[46:47] op_sel_hi:[1,0]
	global_load_dwordx4 v[60:63], v204, s[36:37] offset:128
	global_load_dwordx4 v[32:35], v204, s[36:37] offset:160
	v_pk_fma_f32 v[16:17], v[98:99], v[98:99], v[44:45]
	v_mul_f32_e32 v44, v99, v99
	v_pk_add_f32 v[16:17], v[16:17], v[44:45] op_sel_hi:[1,0]
	global_load_dwordx4 v[40:43], v204, s[36:37] offset:192
	global_load_dwordx4 v[36:39], v204, s[36:37] offset:224
	v_pk_fma_f32 v[16:17], v[100:101], v[100:101], v[16:17]
	s_nop 0
	v_pk_add_f32 v[162:163], v[16:17], v[18:19] op_sel_hi:[1,0]
	global_load_dwordx4 v[44:47], v204, s[36:37] offset:256
	global_load_dwordx4 v[16:19], v204, s[36:37] offset:288
	v_pk_fma_f32 v[20:21], v[102:103], v[102:103], v[162:163]
	v_mul_f32_e32 v162, v103, v103
	v_pk_add_f32 v[20:21], v[20:21], v[162:163] op_sel_hi:[1,0]
	s_nop 0
	v_pk_fma_f32 v[20:21], v[104:105], v[104:105], v[20:21]
	s_nop 0
	v_pk_add_f32 v[20:21], v[20:21], v[22:23] op_sel_hi:[1,0]
	v_mul_f32_e32 v22, v107, v107
	v_pk_fma_f32 v[20:21], v[106:107], v[106:107], v[20:21]
	s_nop 0
	v_pk_add_f32 v[20:21], v[20:21], v[22:23] op_sel_hi:[1,0]
	v_mul_f32_e32 v22, v109, v109
	v_pk_fma_f32 v[20:21], v[108:109], v[108:109], v[20:21]
	s_nop 0
	v_pk_add_f32 v[162:163], v[20:21], v[22:23] op_sel_hi:[1,0]
	global_load_dwordx4 v[24:27], v204, s[36:37] offset:320
	global_load_dwordx4 v[20:23], v204, s[36:37] offset:352
	v_pk_fma_f32 v[132:133], v[28:29], v[28:29], v[162:163]
	v_mul_f32_e32 v162, v29, v29
	v_pk_add_f32 v[132:133], v[132:133], v[162:163] op_sel_hi:[1,0]
	s_nop 0
	v_pk_fma_f32 v[130:131], v[30:31], v[30:31], v[132:133]
	v_mul_f32_e32 v132, v31, v31
	v_pk_add_f32 v[130:131], v[130:131], v[132:133] op_sel_hi:[1,0]
	v_add_u32_e32 v132, s16, v137
	v_pk_fma_f32 v[0:1], v[116:117], v[116:117], v[130:131]
	v_mul_f32_e32 v130, v117, v117
	v_pk_add_f32 v[0:1], v[0:1], v[130:131] op_sel_hi:[1,0]
	v_ashrrev_i32_e32 v133, 31, v132
	v_pk_fma_f32 v[0:1], v[122:123], v[122:123], v[0:1]
	s_nop 0
	v_pk_add_f32 v[0:1], v[0:1], v[2:3] op_sel_hi:[1,0]
	v_mul_f32_e32 v2, v127, v127
	v_pk_fma_f32 v[0:1], v[126:127], v[126:127], v[0:1]
	s_nop 0
	v_pk_add_f32 v[0:1], v[0:1], v[2:3] op_sel_hi:[1,0]
	v_mul_f32_e32 v2, v129, v129
	v_pk_fma_f32 v[0:1], v[128:129], v[128:129], v[0:1]
	s_nop 0
	v_pk_add_f32 v[0:1], v[0:1], v[2:3] op_sel_hi:[1,0]
	v_mul_f32_e32 v2, v125, v125
	v_pk_fma_f32 v[0:1], v[124:125], v[124:125], v[0:1]
	s_nop 0
	v_pk_add_f32 v[0:1], v[0:1], v[2:3] op_sel_hi:[1,0]
	v_mul_f32_e32 v2, v121, v121
	v_pk_fma_f32 v[0:1], v[120:121], v[120:121], v[0:1]
	s_nop 0
	v_pk_add_f32 v[0:1], v[0:1], v[2:3] op_sel_hi:[1,0]
	v_mul_f32_e32 v2, v119, v119
	v_pk_fma_f32 v[0:1], v[118:119], v[118:119], v[0:1]
	s_nop 0
	v_pk_add_f32 v[0:1], v[0:1], v[2:3] op_sel_hi:[1,0]
	v_mul_f32_e32 v2, v115, v115
	v_pk_fma_f32 v[0:1], v[114:115], v[114:115], v[0:1]
	s_nop 0
	v_pk_add_f32 v[0:1], v[0:1], v[2:3] op_sel_hi:[1,0]
	s_nop 0
	v_mov_b32_e32 v1, v0
	s_nop 1
	v_permlane32_swap_b32_e32 v0, v1
	v_add_f32_e32 v0, v0, v1
	v_fmamk_f32 v0, v0, 0x3c000000, v221
	v_mul_f32_e32 v1, 0x4b800000, v0
	v_cmp_gt_f32_e32 vcc, s85, v0
	s_nop 1
	v_cndmask_b32_e32 v0, v0, v1, vcc
	v_rsq_f32_e32 v130, v0
	global_load_dwordx4 v[12:15], v204, s[36:37] offset:384
	global_load_dwordx4 v[8:11], v204, s[36:37] offset:416
	global_load_dwordx4 v[4:7], v204, s[36:37] offset:448
	global_load_dwordx4 v[0:3], v204, s[36:37] offset:480
	v_mul_f32_e32 v131, 0x45800000, v130
	v_cndmask_b32_e32 v130, v130, v131, vcc
	v_mul_f32_e32 v130, v250, v130
	v_pk_mul_f32 v[110:111], v[110:111], v[130:131] op_sel_hi:[1,0]
	v_pk_mul_f32 v[112:113], v[112:113], v[130:131] op_sel_hi:[1,0]
	s_waitcnt vmcnt(15)
	v_pk_mul_f32 v[64:65], v[64:65], v[110:111]
	v_mad_i64_i32 v[110:111], s[0:1], v132, s87, v[76:77]
	v_lshl_add_u64 v[110:111], v[110:111], 0, s[42:43]
	v_lshl_add_u64 v[110:111], v[110:111], 0, v[222:223]
	v_add_co_u32_e32 v110, vcc, s86, v110
	v_pk_mul_f32 v[66:67], v[66:67], v[112:113]
	s_nop 0
	v_addc_co_u32_e32 v111, vcc, 0, v111, vcc
	global_load_dwordx4 v[110:113], v[110:111], off offset:2048
	ds_write_b128 v139, v[64:67] offset:16384
	v_pk_mul_f32 v[64:65], v[68:69], v[130:131] op_sel_hi:[1,0]
	v_pk_mul_f32 v[66:67], v[70:71], v[130:131] op_sel_hi:[1,0]
	s_waitcnt vmcnt(15)
	v_pk_mul_f32 v[48:49], v[48:49], v[64:65]
	v_pk_mul_f32 v[50:51], v[50:51], v[66:67]
	ds_write_b128 v200, v[48:51] offset:16384
	v_pk_mul_f32 v[48:49], v[72:73], v[130:131] op_sel_hi:[1,0]
	v_pk_mul_f32 v[50:51], v[74:75], v[130:131] op_sel_hi:[1,0]
	s_waitcnt vmcnt(14)
	v_pk_mul_f32 v[48:49], v[56:57], v[48:49]
	v_pk_mul_f32 v[50:51], v[58:59], v[50:51]
	ds_write_b128 v201, v[48:51] offset:16384
	v_pk_mul_f32 v[48:49], v[78:79], v[130:131] op_sel_hi:[1,0]
	v_pk_mul_f32 v[50:51], v[80:81], v[130:131] op_sel_hi:[1,0]
	s_waitcnt vmcnt(13)
	v_pk_mul_f32 v[48:49], v[52:53], v[48:49]
	v_pk_mul_f32 v[50:51], v[54:55], v[50:51]
	ds_write_b128 v202, v[48:51] offset:16384
	v_pk_mul_f32 v[48:49], v[82:83], v[130:131] op_sel_hi:[1,0]
	v_pk_mul_f32 v[50:51], v[84:85], v[130:131] op_sel_hi:[1,0]
	s_waitcnt vmcnt(12)
; #define LAS __attribute__((address_space(3)))
; DI unsigned cvtpk(float lo, float hi) { f32x2 v = {lo, hi}; bf16x2_t b = __builtin_convertvector(v, bf16x2_t); return __builtin_bit_cast(unsigned, b); }
; DI void attn_unit(LAS unsigned char* lds, const bf16_t* P, bf16_t* Am, int qrow0, int h, int ntiles, int krow_ctx, int krow_lat,
;                   float lam, const float* subw, float outscale) {
;     ...
;                 for (int rg = 0; rg < 4; ++rg) { const int e0 = 32 * d0 + 8 * rg, cc = 8 * d0 + 2 * rg + hie;
;                     const f32x4 w4 = *(const f32x4*)(subw + e0 + 4 * hie);
;                     const float v0 = half ? ob[d0][4 * rg + 0] : oa[d0][4 * rg + 0], v1 = half ? ob[d0][4 * rg + 1] : oa[d0][4 * rg + 1];
;                     const float v2 = half ? ob[d0][4 * rg + 2] : oa[d0][4 * rg + 2], v3 = half ? ob[d0][4 * rg + 3] : oa[d0][4 * rg + 3];
;                     const f32x4 tv = {v0 * rr * w4[0], v1 * rr * w4[1], v2 * rr * w4[2], v3 * rr * w4[3]};
;                     *(LAS f32x4*)(stg + r32e * 128 + ((cc ^ r32e) & 31) * 4) = tv; }
;             const int k16 = lane2 & 15;
; #pragma unroll
;             for (int i = 0; i < 8; ++i) { const int R = 4 * i + (lane2 >> 4);
;                 const f32x4 ta = *(const LAS f32x4*)(stg + R * 128 + (((2 * k16) ^ R) & 31) * 4), tb = *(const LAS f32x4*)(stg + R * 128 + (((2 * k16 + 1) ^ R) & 31) * 4);
;                 const size_t row = (size_t)(qrow0 + 64 * g + 32 * half + R);
;                 const u32x4 sg = *(const u32x4*)(P + row * DIN + O_AG + h * 128 + 8 * k16);
;                 u32x4 ov; ov.x = cvtpk(ta[0] * bf_lo(sg.x), ta[1] * bf_hi(sg.x)); ov.y = cvtpk(ta[2] * bf_lo(sg.y), ta[3] * bf_hi(sg.y));
;                 ov.z = cvtpk(tb[0] * bf_lo(sg.z), tb[1] * bf_hi(sg.z)); ov.w = cvtpk(tb[2] * bf_lo(sg.w), tb[3] * bf_hi(sg.w));
;                 *(u32x4*)(Am + row * DM + 1024 + h * 128 + 8 * k16) = ov; }
	v_pk_mul_f32 v[48:49], v[60:61], v[48:49]
	v_pk_mul_f32 v[50:51], v[62:63], v[50:51]
	ds_write_b128 v203, v[48:51] offset:16384
	v_pk_mul_f32 v[48:49], v[86:87], v[130:131] op_sel_hi:[1,0]
	v_pk_mul_f32 v[50:51], v[88:89], v[130:131] op_sel_hi:[1,0]
	s_waitcnt vmcnt(11)
	v_pk_mul_f32 v[32:33], v[32:33], v[48:49]
	v_pk_mul_f32 v[34:35], v[34:35], v[50:51]
	ds_write_b128 v205, v[32:35] offset:16384
	v_pk_mul_f32 v[32:33], v[90:91], v[130:131] op_sel_hi:[1,0]
	v_pk_mul_f32 v[34:35], v[92:93], v[130:131] op_sel_hi:[1,0]
	s_waitcnt vmcnt(10)
	v_pk_mul_f32 v[32:33], v[32:33], v[40:41]
	v_pk_mul_f32 v[34:35], v[34:35], v[42:43]
	ds_write_b128 v206, v[32:35] offset:16384
	v_pk_mul_f32 v[32:33], v[94:95], v[130:131] op_sel_hi:[1,0]
	v_pk_mul_f32 v[34:35], v[96:97], v[130:131] op_sel_hi:[1,0]
	s_waitcnt vmcnt(9)
	v_pk_mul_f32 v[32:33], v[32:33], v[36:37]
	v_pk_mul_f32 v[34:35], v[34:35], v[38:39]
	ds_write_b128 v207, v[32:35] offset:16384
	v_pk_mul_f32 v[32:33], v[98:99], v[130:131] op_sel_hi:[1,0]
	v_pk_mul_f32 v[34:35], v[100:101], v[130:131] op_sel_hi:[1,0]
	s_waitcnt vmcnt(8)
	v_pk_mul_f32 v[32:33], v[32:33], v[44:45]
	v_pk_mul_f32 v[34:35], v[34:35], v[46:47]
	ds_write_b128 v208, v[32:35] offset:16384
	v_pk_mul_f32 v[32:33], v[102:103], v[130:131] op_sel_hi:[1,0]
	v_pk_mul_f32 v[34:35], v[104:105], v[130:131] op_sel_hi:[1,0]
	s_waitcnt vmcnt(7)
	v_pk_mul_f32 v[16:17], v[32:33], v[16:17]
	v_pk_mul_f32 v[18:19], v[34:35], v[18:19]
	ds_write_b128 v209, v[16:19] offset:16384
	v_pk_mul_f32 v[16:17], v[106:107], v[130:131] op_sel_hi:[1,0]
	v_pk_mul_f32 v[18:19], v[108:109], v[130:131] op_sel_hi:[1,0]
	s_waitcnt vmcnt(6)
	v_pk_mul_f32 v[16:17], v[16:17], v[24:25]
	v_pk_mul_f32 v[18:19], v[18:19], v[26:27]
	ds_write_b128 v210, v[16:19] offset:16384
	v_pk_mul_f32 v[16:17], v[28:29], v[130:131] op_sel_hi:[1,0]
	v_pk_mul_f32 v[18:19], v[30:31], v[130:131] op_sel_hi:[1,0]
	s_waitcnt vmcnt(5)
	v_pk_mul_f32 v[16:17], v[16:17], v[20:21]
	v_pk_mul_f32 v[18:19], v[18:19], v[22:23]
	ds_write_b128 v211, v[16:19] offset:16384
	v_pk_mul_f32 v[16:17], v[116:117], v[130:131] op_sel_hi:[1,0]
	v_pk_mul_f32 v[18:19], v[122:123], v[130:131] op_sel_hi:[1,0]
	s_waitcnt vmcnt(4)
	v_pk_mul_f32 v[12:13], v[16:17], v[12:13]
	v_pk_mul_f32 v[14:15], v[18:19], v[14:15]
	ds_write_b128 v212, v[12:15] offset:16384
	v_pk_mul_f32 v[12:13], v[126:127], v[130:131] op_sel_hi:[1,0]
	v_pk_mul_f32 v[14:15], v[128:129], v[130:131] op_sel_hi:[1,0]
	s_waitcnt vmcnt(3)
	v_pk_mul_f32 v[8:9], v[12:13], v[8:9]
	v_pk_mul_f32 v[10:11], v[14:15], v[10:11]
	ds_write_b128 v213, v[8:11] offset:16384
	v_pk_mul_f32 v[8:9], v[124:125], v[130:131] op_sel_hi:[1,0]
	v_pk_mul_f32 v[10:11], v[120:121], v[130:131] op_sel_hi:[1,0]
	s_waitcnt vmcnt(2)
	v_pk_mul_f32 v[4:5], v[8:9], v[4:5]
	v_pk_mul_f32 v[6:7], v[10:11], v[6:7]
	ds_write_b128 v184, v[4:7] offset:16384
	v_pk_mul_f32 v[4:5], v[118:119], v[130:131] op_sel_hi:[1,0]
	v_pk_mul_f32 v[6:7], v[114:115], v[130:131] op_sel_hi:[1,0]
	s_waitcnt vmcnt(1)
	v_pk_mul_f32 v[0:1], v[4:5], v[0:1]
	v_pk_mul_f32 v[2:3], v[6:7], v[2:3]
	ds_write_b128 v141, v[0:3] offset:16384
	ds_read_b128 v[0:3], v142 offset:16384
	ds_read_b128 v[4:7], v143 offset:16384
	v_add_u32_e32 v12, s16, v144
	v_ashrrev_i32_e32 v13, 31, v12
	s_waitcnt vmcnt(0)
	v_lshlrev_b32_e32 v8, 16, v110
	v_and_b32_e32 v9, 0xffff0000, v110
	s_waitcnt lgkmcnt(1)
	v_pk_mul_f32 v[0:1], v[0:1], v[8:9]
	v_lshlrev_b32_e32 v8, 16, v111
	v_and_b32_e32 v9, 0xffff0000, v111
	v_pk_mul_f32 v[2:3], v[2:3], v[8:9]
	v_cvt_pk_bf16_f32 v0, v0, v1
	v_cvt_pk_bf16_f32 v1, v2, v3
	v_lshlrev_b32_e32 v2, 16, v112
	v_and_b32_e32 v3, 0xffff0000, v112
	s_waitcnt lgkmcnt(0)
	v_pk_mul_f32 v[2:3], v[4:5], v[2:3]
	v_lshlrev_b32_e32 v4, 16, v113
	v_and_b32_e32 v5, 0xffff0000, v113
	v_pk_mul_f32 v[4:5], v[6:7], v[4:5]
	v_cvt_pk_bf16_f32 v2, v2, v3
	v_cvt_pk_bf16_f32 v3, v4, v5
	v_lshlrev_b64 v[4:5], 12, v[132:133]
	v_lshl_add_u64 v[4:5], s[46:47], 0, v[4:5]
	v_lshl_add_u64 v[4:5], v[4:5], 0, s[42:43]
	v_lshl_add_u64 v[4:5], v[4:5], 0, v[222:223]
	global_store_dwordx4 v[4:5], v[0:3], off offset:2048
	s_nop 1
	v_mad_i64_i32 v[0:1], s[0:1], v12, s87, v[76:77]
	v_lshl_add_u64 v[0:1], v[0:1], 0, s[42:43]
	v_lshl_add_u64 v[0:1], v[0:1], 0, v[222:223]
	v_add_co_u32_e32 v0, vcc, s86, v0
	s_nop 1
	v_addc_co_u32_e32 v1, vcc, 0, v1, vcc
	ds_read_b128 v[4:7], v145 offset:16384
	ds_read_b128 v[8:11], v146 offset:16384
	v_mov_b32_e32 v0, v228
	v_mov_b32_e32 v1, v229
	v_mov_b32_e32 v2, v230
	v_mov_b32_e32 v3, v231
	s_add_u32 s6, s8, 0x9c000
	s_addc_u32 s7, s9, 0
	global_load_dwordx4 v[228:231], v244, s[6:7] offset:2048
	v_lshlrev_b32_e32 v14, 16, v0
	v_and_b32_e32 v15, 0xffff0000, v0
	s_waitcnt lgkmcnt(1)
	v_pk_mul_f32 v[4:5], v[4:5], v[14:15]
	s_nop 0
	v_cvt_pk_bf16_f32 v0, v4, v5
	v_lshlrev_b32_e32 v4, 16, v1
	v_and_b32_e32 v5, 0xffff0000, v1
	v_pk_mul_f32 v[4:5], v[6:7], v[4:5]
	s_nop 0
	v_cvt_pk_bf16_f32 v1, v4, v5
	v_lshlrev_b32_e32 v4, 16, v2
	v_and_b32_e32 v5, 0xffff0000, v2
	s_waitcnt lgkmcnt(0)
	v_pk_mul_f32 v[4:5], v[8:9], v[4:5]
	s_nop 0
	v_cvt_pk_bf16_f32 v2, v4, v5
	v_lshlrev_b32_e32 v4, 16, v3
	v_and_b32_e32 v5, 0xffff0000, v3
	v_pk_mul_f32 v[4:5], v[10:11], v[4:5]
	s_nop 0
	v_cvt_pk_bf16_f32 v3, v4, v5
	v_lshlrev_b64 v[4:5], 12, v[12:13]
	v_lshl_add_u64 v[4:5], s[46:47], 0, v[4:5]
	v_lshl_add_u64 v[4:5], v[4:5], 0, s[42:43]
	v_lshl_add_u64 v[4:5], v[4:5], 0, v[222:223]
	v_add_u32_e32 v12, s16, v147
	global_store_dwordx4 v[4:5], v[0:3], off offset:2048
	v_ashrrev_i32_e32 v13, 31, v12
	s_nop 0
	v_mad_i64_i32 v[0:1], s[0:1], v12, s87, v[76:77]
	v_lshl_add_u64 v[0:1], v[0:1], 0, s[42:43]
	v_lshl_add_u64 v[0:1], v[0:1], 0, v[222:223]
	v_add_co_u32_e32 v0, vcc, s86, v0
	s_nop 1
	v_addc_co_u32_e32 v1, vcc, 0, v1, vcc
	ds_read_b128 v[4:7], v151 offset:16384
	ds_read_b128 v[8:11], v152 offset:16384
	v_mov_b32_e32 v0, v232
	v_mov_b32_e32 v1, v233
	v_mov_b32_e32 v2, v234
	v_mov_b32_e32 v3, v235
	s_add_u32 s6, s8, 0xa8000
	s_addc_u32 s7, s9, 0
	global_load_dwordx4 v[232:235], v244, s[6:7] offset:2048
	v_lshlrev_b32_e32 v14, 16, v0
	v_and_b32_e32 v15, 0xffff0000, v0
	s_waitcnt lgkmcnt(1)
; #define LAS __attribute__((address_space(3)))
; DI unsigned cvtpk(float lo, float hi) { f32x2 v = {lo, hi}; bf16x2_t b = __builtin_convertvector(v, bf16x2_t); return __builtin_bit_cast(unsigned, b); }
; DI void attn_unit(LAS unsigned char* lds, const bf16_t* P, bf16_t* Am, int qrow0, int h, int ntiles, int krow_ctx, int krow_lat,
;                   float lam, const float* subw, float outscale) {
;     ...
;             const int k16 = lane2 & 15;
; #pragma unroll
;             for (int i = 0; i < 8; ++i) { const int R = 4 * i + (lane2 >> 4);
;                 const f32x4 ta = *(const LAS f32x4*)(stg + R * 128 + (((2 * k16) ^ R) & 31) * 4), tb = *(const LAS f32x4*)(stg + R * 128 + (((2 * k16 + 1) ^ R) & 31) * 4);
;                 const size_t row = (size_t)(qrow0 + 64 * g + 32 * half + R);
;                 const u32x4 sg = *(const u32x4*)(P + row * DIN + O_AG + h * 128 + 8 * k16);
;                 u32x4 ov; ov.x = cvtpk(ta[0] * bf_lo(sg.x), ta[1] * bf_hi(sg.x)); ov.y = cvtpk(ta[2] * bf_lo(sg.y), ta[3] * bf_hi(sg.y));
;                 ov.z = cvtpk(tb[0] * bf_lo(sg.z), tb[1] * bf_hi(sg.z)); ov.w = cvtpk(tb[2] * bf_lo(sg.w), tb[3] * bf_hi(sg.w));
;                 *(u32x4*)(Am + row * DM + 1024 + h * 128 + 8 * k16) = ov; }
	v_pk_mul_f32 v[4:5], v[4:5], v[14:15]
	s_nop 0
	v_cvt_pk_bf16_f32 v0, v4, v5
	v_lshlrev_b32_e32 v4, 16, v1
	v_and_b32_e32 v5, 0xffff0000, v1
	v_pk_mul_f32 v[4:5], v[6:7], v[4:5]
	s_nop 0
	v_cvt_pk_bf16_f32 v1, v4, v5
	v_lshlrev_b32_e32 v4, 16, v2
	v_and_b32_e32 v5, 0xffff0000, v2
	s_waitcnt lgkmcnt(0)
	v_pk_mul_f32 v[4:5], v[8:9], v[4:5]
	s_nop 0
	v_cvt_pk_bf16_f32 v2, v4, v5
	v_lshlrev_b32_e32 v4, 16, v3
	v_and_b32_e32 v5, 0xffff0000, v3
	v_pk_mul_f32 v[4:5], v[10:11], v[4:5]
	s_nop 0
	v_cvt_pk_bf16_f32 v3, v4, v5
	v_lshlrev_b64 v[4:5], 12, v[12:13]
	v_lshl_add_u64 v[4:5], s[46:47], 0, v[4:5]
	v_lshl_add_u64 v[4:5], v[4:5], 0, s[42:43]
	v_lshl_add_u64 v[4:5], v[4:5], 0, v[222:223]
	v_add_u32_e32 v12, s16, v153
	global_store_dwordx4 v[4:5], v[0:3], off offset:2048
	v_ashrrev_i32_e32 v13, 31, v12
	s_nop 0
	v_mad_i64_i32 v[0:1], s[0:1], v12, s87, v[76:77]
	v_lshl_add_u64 v[0:1], v[0:1], 0, s[42:43]
	v_lshl_add_u64 v[0:1], v[0:1], 0, v[222:223]
	v_add_co_u32_e32 v0, vcc, s86, v0
	s_nop 1
	v_addc_co_u32_e32 v1, vcc, 0, v1, vcc
	ds_read_b128 v[4:7], v155 offset:16384
	ds_read_b128 v[8:11], v156 offset:16384
	v_mov_b32_e32 v0, v236
	v_mov_b32_e32 v1, v237
	v_mov_b32_e32 v2, v238
	v_mov_b32_e32 v3, v239
	s_add_u32 s6, s8, 0xb4000
	s_addc_u32 s7, s9, 0
	global_load_dwordx4 v[236:239], v244, s[6:7] offset:2048
	v_lshlrev_b32_e32 v14, 16, v0
	v_and_b32_e32 v15, 0xffff0000, v0
	v_lshlrev_b32_e32 v0, 16, v1
	v_and_b32_e32 v1, 0xffff0000, v1
	v_lshlrev_b32_e32 v16, 16, v2
	s_waitcnt lgkmcnt(1)
	v_pk_mul_f32 v[4:5], v[4:5], v[14:15]
	v_and_b32_e32 v17, 0xffff0000, v2
	v_pk_mul_f32 v[6:7], v[6:7], v[0:1]
	v_cvt_pk_bf16_f32 v0, v4, v5
	s_waitcnt lgkmcnt(0)
	v_pk_mul_f32 v[4:5], v[8:9], v[16:17]
	v_cvt_pk_bf16_f32 v1, v6, v7
	v_cvt_pk_bf16_f32 v2, v4, v5
	v_lshlrev_b32_e32 v4, 16, v3
	v_and_b32_e32 v5, 0xffff0000, v3
	v_pk_mul_f32 v[4:5], v[10:11], v[4:5]
	s_nop 0
	v_cvt_pk_bf16_f32 v3, v4, v5
	v_lshlrev_b64 v[4:5], 12, v[12:13]
	v_lshl_add_u64 v[4:5], s[46:47], 0, v[4:5]
	v_lshl_add_u64 v[4:5], v[4:5], 0, s[42:43]
	v_lshl_add_u64 v[4:5], v[4:5], 0, v[222:223]
	global_store_dwordx4 v[4:5], v[0:3], off offset:2048
	v_add_u32_e32 v4, s16, v154
	v_add_u32_e32 v12, s16, v158
	v_mad_i64_i32 v[0:1], s[0:1], v4, s87, v[76:77]
	v_lshl_add_u64 v[0:1], v[0:1], 0, s[42:43]
	v_lshl_add_u64 v[0:1], v[0:1], 0, v[222:223]
	v_add_co_u32_e32 v0, vcc, s86, v0
	v_ashrrev_i32_e32 v5, 31, v4
	s_nop 0
	v_addc_co_u32_e32 v1, vcc, 0, v1, vcc
	v_mad_i64_i32 v[6:7], s[0:1], v12, s87, v[76:77]
	v_lshlrev_b64 v[4:5], 12, v[4:5]
	v_lshl_add_u64 v[6:7], v[6:7], 0, s[42:43]
	v_lshl_add_u64 v[4:5], s[46:47], 0, v[4:5]
	v_lshl_add_u64 v[6:7], v[6:7], 0, v[222:223]
	v_lshl_add_u64 v[4:5], v[4:5], 0, s[42:43]
	v_add_co_u32_e32 v14, vcc, s86, v6
	v_lshl_add_u64 v[16:17], v[4:5], 0, v[222:223]
	s_nop 0
	v_addc_co_u32_e32 v15, vcc, 0, v7, vcc
	ds_read_b128 v[4:7], v138 offset:16384
	ds_read_b128 v[8:11], v140 offset:16384
	v_ashrrev_i32_e32 v13, 31, v12
	v_mov_b32_e32 v0, v240
	v_mov_b32_e32 v1, v241
	v_mov_b32_e32 v2, v242
	v_mov_b32_e32 v3, v243
	v_lshlrev_b32_e32 v18, 16, v0
	v_and_b32_e32 v19, 0xffff0000, v0
	v_lshlrev_b32_e32 v0, 16, v1
	v_and_b32_e32 v1, 0xffff0000, v1
	v_lshlrev_b32_e32 v20, 16, v2
	v_and_b32_e32 v21, 0xffff0000, v2
	v_lshlrev_b32_e32 v2, 16, v3
	v_and_b32_e32 v3, 0xffff0000, v3
	s_waitcnt lgkmcnt(1)
	v_pk_mul_f32 v[4:5], v[4:5], v[18:19]
	v_pk_mul_f32 v[6:7], v[6:7], v[0:1]
	s_waitcnt lgkmcnt(0)
; #define LAS __attribute__((address_space(3)))
; DI unsigned cvtpk(float lo, float hi) { f32x2 v = {lo, hi}; bf16x2_t b = __builtin_convertvector(v, bf16x2_t); return __builtin_bit_cast(unsigned, b); }
; DI void attn_unit(LAS unsigned char* lds, const bf16_t* P, bf16_t* Am, int qrow0, int h, int ntiles, int krow_ctx, int krow_lat,
;                   float lam, const float* subw, float outscale) {
;     ...
;             const int k16 = lane2 & 15;
; #pragma unroll
;             for (int i = 0; i < 8; ++i) { const int R = 4 * i + (lane2 >> 4);
;                 const f32x4 ta = *(const LAS f32x4*)(stg + R * 128 + (((2 * k16) ^ R) & 31) * 4), tb = *(const LAS f32x4*)(stg + R * 128 + (((2 * k16 + 1) ^ R) & 31) * 4);
;                 const size_t row = (size_t)(qrow0 + 64 * g + 32 * half + R);
;                 const u32x4 sg = *(const u32x4*)(P + row * DIN + O_AG + h * 128 + 8 * k16);
;                 u32x4 ov; ov.x = cvtpk(ta[0] * bf_lo(sg.x), ta[1] * bf_hi(sg.x)); ov.y = cvtpk(ta[2] * bf_lo(sg.y), ta[3] * bf_hi(sg.y));
;                 ov.z = cvtpk(tb[0] * bf_lo(sg.z), tb[1] * bf_hi(sg.z)); ov.w = cvtpk(tb[2] * bf_lo(sg.w), tb[3] * bf_hi(sg.w));
;                 *(u32x4*)(Am + row * DM + 1024 + h * 128 + 8 * k16) = ov; }
	v_pk_mul_f32 v[8:9], v[8:9], v[20:21]
	v_pk_mul_f32 v[10:11], v[10:11], v[2:3]
	v_cvt_pk_bf16_f32 v0, v4, v5
	v_cvt_pk_bf16_f32 v1, v6, v7
	v_cvt_pk_bf16_f32 v2, v8, v9
	v_cvt_pk_bf16_f32 v3, v10, v11
	global_store_dwordx4 v[16:17], v[0:3], off offset:2048
	v_add_u32_e32 v14, s16, v157
	v_mad_i64_i32 v[4:5], s[0:1], v14, s87, v[76:77]
	v_lshlrev_b64 v[6:7], 12, v[12:13]
	v_lshl_add_u64 v[4:5], v[4:5], 0, s[42:43]
	v_lshl_add_u64 v[6:7], s[46:47], 0, v[6:7]
	v_lshl_add_u64 v[4:5], v[4:5], 0, v[222:223]
	v_lshl_add_u64 v[6:7], v[6:7], 0, s[42:43]
	v_add_co_u32_e32 v12, vcc, s86, v4
	v_lshl_add_u64 v[16:17], v[6:7], 0, v[222:223]
	s_nop 0
	v_addc_co_u32_e32 v13, vcc, 0, v5, vcc
	ds_read_b128 v[4:7], v134 offset:16384
	ds_read_b128 v[8:11], v135 offset:16384
	v_ashrrev_i32_e32 v15, 31, v14
	s_waitcnt vmcnt(6)
	v_mov_b32_e32 v0, v228
	v_mov_b32_e32 v1, v229
	v_mov_b32_e32 v2, v230
	v_mov_b32_e32 v3, v231
	v_lshlrev_b32_e32 v18, 16, v0
	v_and_b32_e32 v19, 0xffff0000, v0
	v_lshlrev_b32_e32 v0, 16, v1
	v_and_b32_e32 v1, 0xffff0000, v1
	v_lshlrev_b32_e32 v20, 16, v2
	v_and_b32_e32 v21, 0xffff0000, v2
	v_lshlrev_b32_e32 v2, 16, v3
	v_and_b32_e32 v3, 0xffff0000, v3
	s_waitcnt lgkmcnt(1)
	v_pk_mul_f32 v[4:5], v[4:5], v[18:19]
	v_pk_mul_f32 v[6:7], v[6:7], v[0:1]
	s_waitcnt lgkmcnt(0)
	v_pk_mul_f32 v[8:9], v[8:9], v[20:21]
	v_pk_mul_f32 v[10:11], v[10:11], v[2:3]
	v_cvt_pk_bf16_f32 v0, v4, v5
	v_cvt_pk_bf16_f32 v1, v6, v7
	v_cvt_pk_bf16_f32 v2, v8, v9
	v_cvt_pk_bf16_f32 v3, v10, v11
	global_store_dwordx4 v[16:17], v[0:3], off offset:2048
	v_add_u32_e32 v12, s16, v149
	v_mad_i64_i32 v[4:5], s[0:1], v12, s87, v[76:77]
	v_lshlrev_b64 v[6:7], 12, v[14:15]
	v_lshl_add_u64 v[4:5], v[4:5], 0, s[42:43]
	v_lshl_add_u64 v[6:7], s[46:47], 0, v[6:7]
	v_lshl_add_u64 v[4:5], v[4:5], 0, v[222:223]
	v_lshl_add_u64 v[6:7], v[6:7], 0, s[42:43]
	v_add_co_u32_e32 v14, vcc, s86, v4
	v_lshl_add_u64 v[16:17], v[6:7], 0, v[222:223]
	s_nop 0
	v_addc_co_u32_e32 v15, vcc, 0, v5, vcc
	ds_read_b128 v[4:7], v148 offset:16384
	ds_read_b128 v[8:11], v150 offset:16384
	v_ashrrev_i32_e32 v13, 31, v12
	s_waitcnt vmcnt(5)
	v_mov_b32_e32 v0, v232
	v_mov_b32_e32 v1, v233
	v_mov_b32_e32 v2, v234
	v_mov_b32_e32 v3, v235
	v_lshlrev_b32_e32 v18, 16, v0
	v_and_b32_e32 v19, 0xffff0000, v0
	v_lshlrev_b32_e32 v0, 16, v1
	v_and_b32_e32 v1, 0xffff0000, v1
	v_lshlrev_b32_e32 v20, 16, v2
	v_and_b32_e32 v21, 0xffff0000, v2
	v_lshlrev_b32_e32 v2, 16, v3
	v_and_b32_e32 v3, 0xffff0000, v3
	s_waitcnt lgkmcnt(1)
	v_pk_mul_f32 v[4:5], v[4:5], v[18:19]
	v_pk_mul_f32 v[6:7], v[6:7], v[0:1]
	s_waitcnt lgkmcnt(0)
	v_pk_mul_f32 v[8:9], v[8:9], v[20:21]
	v_pk_mul_f32 v[10:11], v[10:11], v[2:3]
	v_cvt_pk_bf16_f32 v0, v4, v5
	v_cvt_pk_bf16_f32 v1, v6, v7
	v_cvt_pk_bf16_f32 v2, v8, v9
	v_cvt_pk_bf16_f32 v3, v10, v11
	global_store_dwordx4 v[16:17], v[0:3], off offset:2048
	v_lshlrev_b64 v[4:5], 12, v[12:13]
	v_lshl_add_u64 v[4:5], s[46:47], 0, v[4:5]
	v_lshl_add_u64 v[12:13], v[4:5], 0, s[42:43]
	ds_read_b128 v[4:7], v159 offset:16384
	ds_read_b128 v[8:11], v160 offset:16384
	s_waitcnt vmcnt(4)
	v_mov_b32_e32 v0, v236
	v_mov_b32_e32 v1, v237
	v_mov_b32_e32 v2, v238
	v_mov_b32_e32 v3, v239
	v_lshlrev_b32_e32 v14, 16, v0
	v_and_b32_e32 v15, 0xffff0000, v0
	v_lshlrev_b32_e32 v0, 16, v1
	v_and_b32_e32 v1, 0xffff0000, v1
	v_lshlrev_b32_e32 v16, 16, v2
	v_and_b32_e32 v17, 0xffff0000, v2
	v_lshlrev_b32_e32 v2, 16, v3
	v_and_b32_e32 v3, 0xffff0000, v3
	s_waitcnt lgkmcnt(1)
	v_pk_mul_f32 v[4:5], v[4:5], v[14:15]
	v_pk_mul_f32 v[6:7], v[6:7], v[0:1]
	s_waitcnt lgkmcnt(0)
	v_pk_mul_f32 v[8:9], v[8:9], v[16:17]
	v_pk_mul_f32 v[10:11], v[10:11], v[2:3]
	v_cvt_pk_bf16_f32 v0, v4, v5
	v_cvt_pk_bf16_f32 v1, v6, v7
	v_cvt_pk_bf16_f32 v2, v8, v9
	v_cvt_pk_bf16_f32 v3, v10, v11
	v_lshl_add_u64 v[4:5], v[12:13], 0, v[222:223]
	global_store_dwordx4 v[4:5], v[0:3], off offset:2048
	s_branch .LBB0_325
